# QK gather prefetch depth 2 -> 6 tiles (7 K buffers)
# speedup vs baseline: 1.0001x; 1.0001x over previous
; #define LAS __attribute__((address_space(3)))
; __device__ __forceinline__ void dsa_unit(int wv, const Args& A, LAS unsigned char* lds, int s, int qt) {
;     ...
;         const int qq = 2 * w + qi2; int n = __builtin_amdgcn_readfirstlane((int)cnt[qq]); n = n > 256 ? 256 : n;
;         const size_t qrow = qrow0 + qq; const int qpos = qpos0 + qq;
;         LAS const unsigned short* lst = ci + qq * CAP;
;         long qf[8];
; #pragma unroll
;         for (int kk = 0; kk < 8; ++kk) { qf[kk] = 0;
;             if (fr < 8 && (fr >> 2) == (kk >> 2)) { const h16x8 q = __builtin_bit_cast(h16x8, *(const u32x4*)(PROJ + qrow * PW + C_Q + fr * 128 + ((kk >> 1) & 1) * 64 + fq * 16 + (kk & 1) * 8));
;                 f32x4 a, bq;
; #pragma unroll
;                 for (int e = 0; e < 4; ++e) { a[e] = 16.f * (float)q[e]; bq[e] = 16.f * (float)q[4 + e]; }
;                 qf[kk] = __builtin_bit_cast(long, pack_fp8x8(a, bq)); } }
;         const int nt = n >> 4;
.LBB0_1429:
	s_or_b32 s1, s0, s94
	s_lshl_b32 s12, s1, 2
	s_add_i32 s12, s12, 0
	s_add_i32 s12, s12, 0x1c800
	v_mov_b32_e32 v0, s12
	ds_read_b32 v0, v0
	s_ashr_i32 s12, s1, 31
	s_add_u32 s22, s1, s5
	s_addc_u32 s23, s12, 0
	s_mul_i32 s14, s23, 0x2e00
	v_mad_u64_u32 v[2:3], s[12:13], s22, v157, v[22:23]
	s_waitcnt lgkmcnt(0)
	v_readfirstlane_b32 s30, v0
	v_add_u32_e32 v3, s14, v3
	v_mov_b64_e32 v[32:33], 0
	v_mov_b64_e32 v[34:35], 0
	v_mov_b64_e32 v[36:37], 0
	v_mov_b64_e32 v[38:39], 0
	v_mov_b64_e32 v[40:41], 0
	v_mov_b64_e32 v[42:43], 0
	v_mov_b64_e32 v[44:45], 0
	v_mov_b64_e32 v[46:47], 0
	s_or_b64 s[14:15], s[10:11], s[20:21]
	s_and_saveexec_b64 s[12:13], s[14:15]
	global_load_dwordx4 v[56:59], v[2:3], off
	global_load_dwordx4 v[60:63], v[2:3], off offset:16
	global_load_dwordx4 v[64:67], v[2:3], off offset:128
	global_load_dwordx4 v[68:71], v[2:3], off offset:144
	s_waitcnt vmcnt(3)
	v_cvt_f32_f16_e32 v145, v56
	v_cvt_f32_f16_e32 v146, v58
	v_cvt_f32_f16_sdwa v147, v56 dst_sel:DWORD dst_unused:UNUSED_PAD src0_sel:WORD_1
	v_cvt_f32_f16_sdwa v148, v58 dst_sel:DWORD dst_unused:UNUSED_PAD src0_sel:WORD_1
	v_mul_f32_e32 v145, 0x41800000, v145
	v_mul_f32_e32 v146, 0x41800000, v146
	v_mul_f32_e32 v147, 0x41800000, v147
	v_mul_f32_e32 v148, 0x41800000, v148
	v_cvt_f32_f16_e32 v149, v57
	v_cvt_f32_f16_e32 v158, v59
	v_cvt_f32_f16_sdwa v159, v57 dst_sel:DWORD dst_unused:UNUSED_PAD src0_sel:WORD_1
	v_cvt_f32_f16_sdwa v160, v59 dst_sel:DWORD dst_unused:UNUSED_PAD src0_sel:WORD_1
	v_cvt_pk_fp8_f32 v72, v145, v147
	v_cvt_pk_fp8_f32 v73, v146, v148
	v_mul_f32_e32 v149, 0x41800000, v149
	v_mul_f32_e32 v158, 0x41800000, v158
	v_mul_f32_e32 v159, 0x41800000, v159
	v_mul_f32_e32 v160, 0x41800000, v160
	v_cvt_pk_fp8_f32 v72, v149, v159 op_sel:[0,0,1]
	v_cvt_pk_fp8_f32 v73, v158, v160 op_sel:[0,0,1]
	s_waitcnt vmcnt(2)
	v_cvt_f32_f16_e32 v145, v60
	v_cvt_f32_f16_e32 v146, v62
	v_cvt_f32_f16_sdwa v147, v60 dst_sel:DWORD dst_unused:UNUSED_PAD src0_sel:WORD_1
	v_cvt_f32_f16_sdwa v148, v62 dst_sel:DWORD dst_unused:UNUSED_PAD src0_sel:WORD_1
	v_mul_f32_e32 v145, 0x41800000, v145
	v_mul_f32_e32 v146, 0x41800000, v146
	v_mul_f32_e32 v147, 0x41800000, v147
	v_mul_f32_e32 v148, 0x41800000, v148
	v_cvt_f32_f16_e32 v149, v61
	v_cvt_f32_f16_e32 v158, v63
	v_cvt_f32_f16_sdwa v159, v61 dst_sel:DWORD dst_unused:UNUSED_PAD src0_sel:WORD_1
	v_cvt_f32_f16_sdwa v160, v63 dst_sel:DWORD dst_unused:UNUSED_PAD src0_sel:WORD_1
	v_cvt_pk_fp8_f32 v74, v145, v147
	v_cvt_pk_fp8_f32 v75, v146, v148
	v_mul_f32_e32 v149, 0x41800000, v149
	v_mul_f32_e32 v158, 0x41800000, v158
	v_mul_f32_e32 v159, 0x41800000, v159
	v_mul_f32_e32 v160, 0x41800000, v160
	v_cvt_pk_fp8_f32 v74, v149, v159 op_sel:[0,0,1]
	v_cvt_pk_fp8_f32 v75, v158, v160 op_sel:[0,0,1]
	s_waitcnt vmcnt(1)
	v_cvt_f32_f16_e32 v145, v64
	v_cvt_f32_f16_e32 v146, v66
	v_cvt_f32_f16_sdwa v147, v64 dst_sel:DWORD dst_unused:UNUSED_PAD src0_sel:WORD_1
	v_cvt_f32_f16_sdwa v148, v66 dst_sel:DWORD dst_unused:UNUSED_PAD src0_sel:WORD_1
	v_mul_f32_e32 v145, 0x41800000, v145
	v_mul_f32_e32 v146, 0x41800000, v146
	v_mul_f32_e32 v147, 0x41800000, v147
	v_mul_f32_e32 v148, 0x41800000, v148
	v_cvt_f32_f16_e32 v149, v65
	v_cvt_f32_f16_e32 v158, v67
	v_cvt_f32_f16_sdwa v159, v65 dst_sel:DWORD dst_unused:UNUSED_PAD src0_sel:WORD_1
	v_cvt_f32_f16_sdwa v160, v67 dst_sel:DWORD dst_unused:UNUSED_PAD src0_sel:WORD_1
	v_cvt_pk_fp8_f32 v76, v145, v147
	v_cvt_pk_fp8_f32 v77, v146, v148
	v_mul_f32_e32 v149, 0x41800000, v149
	v_mul_f32_e32 v158, 0x41800000, v158
	v_mul_f32_e32 v159, 0x41800000, v159
	v_mul_f32_e32 v160, 0x41800000, v160
	v_cvt_pk_fp8_f32 v76, v149, v159 op_sel:[0,0,1]
	v_cvt_pk_fp8_f32 v77, v158, v160 op_sel:[0,0,1]
	s_waitcnt vmcnt(0)
	v_cvt_f32_f16_e32 v145, v68
	v_cvt_f32_f16_e32 v146, v70
	v_cvt_f32_f16_sdwa v147, v68 dst_sel:DWORD dst_unused:UNUSED_PAD src0_sel:WORD_1
	v_cvt_f32_f16_sdwa v148, v70 dst_sel:DWORD dst_unused:UNUSED_PAD src0_sel:WORD_1
	v_mul_f32_e32 v145, 0x41800000, v145
	v_mul_f32_e32 v146, 0x41800000, v146
	v_mul_f32_e32 v147, 0x41800000, v147
	v_mul_f32_e32 v148, 0x41800000, v148
	v_cvt_f32_f16_e32 v149, v69
	v_cvt_f32_f16_e32 v158, v71
	v_cvt_f32_f16_sdwa v159, v69 dst_sel:DWORD dst_unused:UNUSED_PAD src0_sel:WORD_1
	v_cvt_f32_f16_sdwa v160, v71 dst_sel:DWORD dst_unused:UNUSED_PAD src0_sel:WORD_1
	v_cvt_pk_fp8_f32 v78, v145, v147
	v_cvt_pk_fp8_f32 v79, v146, v148
	v_mul_f32_e32 v149, 0x41800000, v149
	v_mul_f32_e32 v158, 0x41800000, v158
	v_mul_f32_e32 v159, 0x41800000, v159
	v_mul_f32_e32 v160, 0x41800000, v160
	v_cvt_pk_fp8_f32 v78, v149, v159 op_sel:[0,0,1]
	v_cvt_pk_fp8_f32 v79, v158, v160 op_sel:[0,0,1]
	s_nop 0
	v_cndmask_b32_e64 v34, 0, v72, s[10:11]
	v_cndmask_b32_e64 v35, 0, v73, s[10:11]
	v_cndmask_b32_e64 v42, 0, v72, s[20:21]
	v_cndmask_b32_e64 v43, 0, v73, s[20:21]
	v_cndmask_b32_e64 v32, 0, v74, s[10:11]
	v_cndmask_b32_e64 v33, 0, v75, s[10:11]
	v_cndmask_b32_e64 v40, 0, v74, s[20:21]
	v_cndmask_b32_e64 v41, 0, v75, s[20:21]
	v_cndmask_b32_e64 v38, 0, v76, s[10:11]
	v_cndmask_b32_e64 v39, 0, v77, s[10:11]
	v_cndmask_b32_e64 v46, 0, v76, s[20:21]
	v_cndmask_b32_e64 v47, 0, v77, s[20:21]
	v_cndmask_b32_e64 v36, 0, v78, s[10:11]
	v_cndmask_b32_e64 v37, 0, v79, s[10:11]
	v_cndmask_b32_e64 v44, 0, v78, s[20:21]
	v_cndmask_b32_e64 v45, 0, v79, s[20:21]
	s_or_b64 exec, exec, s[12:13]
	s_min_i32 s29, s30, 0x100
	s_ashr_i32 s16, s29, 4
	s_cmp_lt_i32 s16, 1
	s_mulk_i32 s0, 0x980
	s_cbranch_scc1 .LBB0_1458
; __device__ __forceinline__ void dsa_unit(int wv, const Args& A, LAS unsigned char* lds, int s, int qt) {
;     ...
;         DSA_LOADT(kf, 0);
;         for (int kt = 0; kt < nt; ++kt) {
;             long k1[8];
;             DSA_LOADT(k1, kt + 1);
	s_mul_i32 s12, s1, 0x980
	s_add_i32 s1, s1, s4
	v_lshl_add_u32 v141, v94, 1, s12
	v_add_u32_e32 v141, 0x13000, v141
	ds_read_u16 v107, v141
	ds_read_u16 v108, v141 offset:32
	ds_read_u16 v109, v141 offset:64
	ds_read_u16 v110, v141 offset:96
	ds_read_u16 v111, v141 offset:128
	ds_read_u16 v112, v141 offset:160
	ds_read_u16 v113, v141 offset:192
	ds_read_u16 v114, v141 offset:224
	ds_read_u16 v115, v141 offset:256
	ds_read_u16 v116, v141 offset:288
	ds_read_u16 v117, v141 offset:320
	ds_read_u16 v118, v141 offset:352
	ds_read_u16 v119, v141 offset:384
	ds_read_u16 v120, v141 offset:416
	ds_read_u16 v121, v141 offset:448
	ds_read_u16 v122, v141 offset:480
	v_add_u32_e32 v142, s0, v104
	v_add_u32_e32 v142, 0x13000, v142
	v_add_u32_e32 v143, 0x1cc80, v103
	v_mbcnt_lo_u32_b32 v144, -1, 0
	v_mbcnt_hi_u32_b32 v144, -1, v144
	v_lshrrev_b32_e32 v144, 4, v144
	v_lshlrev_b32_e32 v144, 4, v144
	s_waitcnt lgkmcnt(0)
	v_add_lshl_u32 v107, s48, v107, 8
	v_add_u32_e32 v107, v144, v107
	global_load_dwordx4 v[56:59], v107, s[84:85]
	global_load_dwordx4 v[60:63], v107, s[84:85] offset:64
	global_load_dwordx4 v[64:67], v107, s[84:85] offset:128
	global_load_dwordx4 v[68:71], v107, s[84:85] offset:192
	s_cmp_gt_i32 s16, 1
	s_cbranch_scc0 .Lqk_ni_pre
	v_add_lshl_u32 v108, s48, v108, 8
	v_add_u32_e32 v108, v144, v108
	global_load_dwordx4 v[72:75], v108, s[84:85]
	global_load_dwordx4 v[76:79], v108, s[84:85] offset:64
	global_load_dwordx4 v[80:83], v108, s[84:85] offset:128
	global_load_dwordx4 v[84:87], v108, s[84:85] offset:192
	s_cmp_gt_i32 s16, 2
	s_cbranch_scc0 .Lqk_ni_pre
	v_add_lshl_u32 v109, s48, v109, 8
	v_add_u32_e32 v109, v144, v109
	global_load_dwordx4 v[124:127], v109, s[84:85]
	global_load_dwordx4 v[128:131], v109, s[84:85] offset:64
	global_load_dwordx4 v[132:135], v109, s[84:85] offset:128
	global_load_dwordx4 v[136:139], v109, s[84:85] offset:192
	s_cmp_gt_i32 s16, 3
	s_cbranch_scc0 .Lqk_ni_pre
	v_add_lshl_u32 v110, s48, v110, 8
	v_add_u32_e32 v110, v144, v110
	global_load_dwordx4 v[180:183], v110, s[84:85]
	global_load_dwordx4 v[184:187], v110, s[84:85] offset:64
	global_load_dwordx4 v[188:191], v110, s[84:85] offset:128
	global_load_dwordx4 v[192:195], v110, s[84:85] offset:192
	s_cmp_gt_i32 s16, 4
	s_cbranch_scc0 .Lqk_ni_pre
	v_add_lshl_u32 v111, s48, v111, 8
	v_add_u32_e32 v111, v144, v111
	global_load_dwordx4 v[196:199], v111, s[84:85]
	global_load_dwordx4 v[200:203], v111, s[84:85] offset:64
	global_load_dwordx4 v[204:207], v111, s[84:85] offset:128
	global_load_dwordx4 v[208:211], v111, s[84:85] offset:192
	s_cmp_gt_i32 s16, 5
	s_cbranch_scc0 .Lqk_ni_pre
	v_add_lshl_u32 v112, s48, v112, 8
	v_add_u32_e32 v112, v144, v112
	global_load_dwordx4 v[212:215], v112, s[84:85]
	global_load_dwordx4 v[216:219], v112, s[84:85] offset:64
	global_load_dwordx4 v[220:223], v112, s[84:85] offset:128
	global_load_dwordx4 v[224:227], v112, s[84:85] offset:192
.Lqk_ni_pre:
	ds_read_b64 v[92:93], v142
	s_cmp_gt_i32 s16, 6
	s_cbranch_scc0 .Lqk_n6_0
	v_add_lshl_u32 v113, s48, v113, 8
	v_add_u32_e32 v113, v144, v113
	global_load_dwordx4 v[240:243], v113, s[84:85]
	global_load_dwordx4 v[244:247], v113, s[84:85] offset:64
	global_load_dwordx4 v[248:251], v113, s[84:85] offset:128
	global_load_dwordx4 v[252:255], v113, s[84:85] offset:192
	s_waitcnt vmcnt(24)
	s_branch .Lqk_go_0
.Lqk_n6_0:
	s_cmp_gt_i32 s16, 5
	s_cbranch_scc0 .Lqk_n5_0
	s_waitcnt vmcnt(20)
	s_branch .Lqk_go_0
.Lqk_n5_0:
	s_cmp_gt_i32 s16, 4
	s_cbranch_scc0 .Lqk_n4_0
	s_waitcnt vmcnt(16)
	s_branch .Lqk_go_0
.Lqk_n4_0:
	s_cmp_gt_i32 s16, 3
	s_cbranch_scc0 .Lqk_n3_0
	s_waitcnt vmcnt(12)
	s_branch .Lqk_go_0
.Lqk_n3_0:
	s_cmp_gt_i32 s16, 2
	s_cbranch_scc0 .Lqk_n2_0
	s_waitcnt vmcnt(8)
	s_branch .Lqk_go_0

; __device__ __forceinline__ void dsa_unit(int wv, const Args& A, LAS unsigned char* lds, int s, int qt) {
;     ...
;         for (int kt = 0; kt < nt; ++kt) {
;             long k1[8];
;             DSA_LOADT(k1, kt + 1);
;             f32x4 a = {0.f, 0.f, 0.f, 0.f};
; #pragma unroll
;             for (int kk = 0; kk < 8; ++kk) a = __builtin_amdgcn_mfma_f32_16x16x32_fp8_fp8(kf[kk], qf[kk], a, 0, 0, 0);
;             if (fr < 8) {
; #pragma unroll
;                 for (int r = 0; r < 4; ++r) { const int e2 = kt * 16 + fq * 4 + r; const int key2 = lst[e2];
;                     Pw[e2 * 8 + fr] = (h16)(a[r] * 0.0625f + relb[rel_bucket(key2 - qpos) * 8 + fr]); } }
.Lqk_go_0:
	v_mfma_f32_16x16x32_fp8_fp8 v[88:91], v[56:57], v[34:35], 0
	v_mfma_f32_16x16x32_fp8_fp8 v[88:91], v[58:59], v[32:33], v[88:91]
	v_mfma_f32_16x16x32_fp8_fp8 v[88:91], v[60:61], v[38:39], v[88:91]
	v_mfma_f32_16x16x32_fp8_fp8 v[88:91], v[62:63], v[36:37], v[88:91]
	v_mfma_f32_16x16x32_fp8_fp8 v[88:91], v[64:65], v[42:43], v[88:91]
	v_mfma_f32_16x16x32_fp8_fp8 v[88:91], v[66:67], v[40:41], v[88:91]
	v_mfma_f32_16x16x32_fp8_fp8 v[88:91], v[68:69], v[46:47], v[88:91]
	v_mfma_f32_16x16x32_fp8_fp8 v[88:91], v[70:71], v[44:45], v[88:91]
	s_and_saveexec_b64 s[12:13], s[8:9]
	s_waitcnt lgkmcnt(0)
	v_and_b32_e32 v145, 0xffff, v92
	v_lshrrev_b32_e32 v146, 16, v92
	v_and_b32_e32 v147, 0xffff, v93
	v_lshrrev_b32_e32 v148, 16, v93
	v_subrev_u32_e32 v145, s1, v145
	v_subrev_u32_e32 v146, s1, v146
	v_subrev_u32_e32 v147, s1, v147
	v_subrev_u32_e32 v148, s1, v148
	v_sub_u32_e32 v149, 0, v145
	v_sub_u32_e32 v158, 0, v146
	v_sub_u32_e32 v159, 0, v147
	v_sub_u32_e32 v160, 0, v148
	v_max_i32_e32 v149, v145, v149
	v_max_i32_e32 v158, v146, v158
	v_max_i32_e32 v159, v147, v159
	v_max_i32_e32 v160, v148, v160
	v_mul_u32_u24_e32 v161, v149, v149
	v_mul_u32_u24_e32 v162, v158, v158
	v_mul_u32_u24_e32 v163, v159, v159
	v_mul_u32_u24_e32 v164, v160, v160
	v_cvt_f32_u32_e32 v161, v161
	v_cvt_f32_u32_e32 v162, v162
	v_cvt_f32_u32_e32 v163, v163
	v_cvt_f32_u32_e32 v164, v164
	v_lshrrev_b32_e32 v161, 23, v161
	v_lshrrev_b32_e32 v162, 23, v162
	v_lshrrev_b32_e32 v163, 23, v163
	v_lshrrev_b32_e32 v164, 23, v164
	v_add_u32_e32 v161, 0xffffff83, v161
	v_add_u32_e32 v162, 0xffffff83, v162
	v_add_u32_e32 v163, 0xffffff83, v163
	v_add_u32_e32 v164, 0xffffff83, v164
	v_min_u32_e32 v161, 15, v161
	v_min_u32_e32 v162, 15, v162
	v_min_u32_e32 v163, 15, v163
	v_min_u32_e32 v164, 15, v164
	v_cmp_gt_u32_e32 vcc, 8, v149
	v_cmp_gt_u32_e64 s[26:27], 8, v158
	v_cmp_gt_u32_e64 s[36:37], 8, v159
	v_cmp_gt_u32_e64 s[38:39], 8, v160
	v_med3_i32 v165, v145, 0, 1
	v_med3_i32 v166, v146, 0, 1
	v_med3_i32 v167, v147, 0, 1
	v_med3_i32 v168, v148, 0, 1
	v_cndmask_b32_e64 v161, v161, v149, vcc
	v_cndmask_b32_e64 v162, v162, v158, s[26:27]
	v_cndmask_b32_e64 v163, v163, v159, s[36:37]
	v_cndmask_b32_e64 v164, v164, v160, s[38:39]
	v_lshl_add_u32 v161, v165, 4, v161
	v_lshl_add_u32 v162, v166, 4, v162
	v_lshl_add_u32 v163, v167, 4, v163
	v_lshl_add_u32 v164, v168, 4, v164
	v_lshl_add_u32 v165, v161, 5, v25
	v_lshl_add_u32 v166, v162, 5, v25
	v_lshl_add_u32 v167, v163, 5, v25
	v_lshl_add_u32 v168, v164, 5, v25
	ds_read_b32 v165, v165
	ds_read_b32 v166, v166
	ds_read_b32 v167, v167
	ds_read_b32 v168, v168
	s_waitcnt lgkmcnt(3)
	v_fma_mixlo_f16 v165, v88, s3, v165
	s_waitcnt lgkmcnt(2)
	v_fma_mixlo_f16 v166, v89, s3, v166
	s_waitcnt lgkmcnt(1)
	v_fma_mixlo_f16 v167, v90, s3, v167
	s_waitcnt lgkmcnt(0)
	v_fma_mixlo_f16 v168, v91, s3, v168
	ds_write_b16 v143, v165
	ds_write_b16 v143, v166 offset:16
	ds_write_b16 v143, v167 offset:32
	ds_write_b16 v143, v168 offset:48
	s_mov_b64 exec, s[12:13]
	s_cmp_le_i32 s16, 1
	s_cbranch_scc1 .Lqk_done
	ds_read_b64 v[92:93], v142 offset:32
	s_cmp_gt_i32 s16, 7
	s_cbranch_scc0 .Lqk_n6_1
	v_add_lshl_u32 v114, s48, v114, 8
	v_add_u32_e32 v114, v144, v114
	global_load_dwordx4 v[56:59], v114, s[84:85]
	global_load_dwordx4 v[60:63], v114, s[84:85] offset:64
	global_load_dwordx4 v[64:67], v114, s[84:85] offset:128
	global_load_dwordx4 v[68:71], v114, s[84:85] offset:192
	s_waitcnt vmcnt(24)
	s_branch .Lqk_go_1
.Lqk_n6_1:
	s_cmp_gt_i32 s16, 6
	s_cbranch_scc0 .Lqk_n5_1
	s_waitcnt vmcnt(20)
	s_branch .Lqk_go_1
.Lqk_n5_1:
	s_cmp_gt_i32 s16, 5
	s_cbranch_scc0 .Lqk_n4_1
	s_waitcnt vmcnt(16)
	s_branch .Lqk_go_1
.Lqk_n4_1:
	s_cmp_gt_i32 s16, 4
	s_cbranch_scc0 .Lqk_n3_1
	s_waitcnt vmcnt(12)
	s_branch .Lqk_go_1
.Lqk_n3_1:
	s_cmp_gt_i32 s16, 3
	s_cbranch_scc0 .Lqk_n2_1
	s_waitcnt vmcnt(8)
	s_branch .Lqk_go_1

; __device__ __forceinline__ void dsa_unit(int wv, const Args& A, LAS unsigned char* lds, int s, int qt) {
;     ...
;         for (int kt = 0; kt < nt; ++kt) {
;             long k1[8];
;             DSA_LOADT(k1, kt + 1);
;             f32x4 a = {0.f, 0.f, 0.f, 0.f};
; #pragma unroll
;             for (int kk = 0; kk < 8; ++kk) a = __builtin_amdgcn_mfma_f32_16x16x32_fp8_fp8(kf[kk], qf[kk], a, 0, 0, 0);
;             if (fr < 8) {
; #pragma unroll
;                 for (int r = 0; r < 4; ++r) { const int e2 = kt * 16 + fq * 4 + r; const int key2 = lst[e2];
;                     Pw[e2 * 8 + fr] = (h16)(a[r] * 0.0625f + relb[rel_bucket(key2 - qpos) * 8 + fr]); } }
.Lqk_go_1:
	v_mfma_f32_16x16x32_fp8_fp8 v[88:91], v[72:73], v[34:35], 0
	v_mfma_f32_16x16x32_fp8_fp8 v[88:91], v[74:75], v[32:33], v[88:91]
	v_mfma_f32_16x16x32_fp8_fp8 v[88:91], v[76:77], v[38:39], v[88:91]
	v_mfma_f32_16x16x32_fp8_fp8 v[88:91], v[78:79], v[36:37], v[88:91]
	v_mfma_f32_16x16x32_fp8_fp8 v[88:91], v[80:81], v[42:43], v[88:91]
	v_mfma_f32_16x16x32_fp8_fp8 v[88:91], v[82:83], v[40:41], v[88:91]
	v_mfma_f32_16x16x32_fp8_fp8 v[88:91], v[84:85], v[46:47], v[88:91]
	v_mfma_f32_16x16x32_fp8_fp8 v[88:91], v[86:87], v[44:45], v[88:91]
	s_and_saveexec_b64 s[12:13], s[8:9]
	s_waitcnt lgkmcnt(0)
	v_and_b32_e32 v145, 0xffff, v92
	v_lshrrev_b32_e32 v146, 16, v92
	v_and_b32_e32 v147, 0xffff, v93
	v_lshrrev_b32_e32 v148, 16, v93
	v_subrev_u32_e32 v145, s1, v145
	v_subrev_u32_e32 v146, s1, v146
	v_subrev_u32_e32 v147, s1, v147
	v_subrev_u32_e32 v148, s1, v148
	v_sub_u32_e32 v149, 0, v145
	v_sub_u32_e32 v158, 0, v146
	v_sub_u32_e32 v159, 0, v147
	v_sub_u32_e32 v160, 0, v148
	v_max_i32_e32 v149, v145, v149
	v_max_i32_e32 v158, v146, v158
	v_max_i32_e32 v159, v147, v159
	v_max_i32_e32 v160, v148, v160
	v_mul_u32_u24_e32 v161, v149, v149
	v_mul_u32_u24_e32 v162, v158, v158
	v_mul_u32_u24_e32 v163, v159, v159
	v_mul_u32_u24_e32 v164, v160, v160
	v_cvt_f32_u32_e32 v161, v161
	v_cvt_f32_u32_e32 v162, v162
	v_cvt_f32_u32_e32 v163, v163
	v_cvt_f32_u32_e32 v164, v164
	v_lshrrev_b32_e32 v161, 23, v161
	v_lshrrev_b32_e32 v162, 23, v162
	v_lshrrev_b32_e32 v163, 23, v163
	v_lshrrev_b32_e32 v164, 23, v164
	v_add_u32_e32 v161, 0xffffff83, v161
	v_add_u32_e32 v162, 0xffffff83, v162
	v_add_u32_e32 v163, 0xffffff83, v163
	v_add_u32_e32 v164, 0xffffff83, v164
	v_min_u32_e32 v161, 15, v161
	v_min_u32_e32 v162, 15, v162
	v_min_u32_e32 v163, 15, v163
	v_min_u32_e32 v164, 15, v164
	v_cmp_gt_u32_e32 vcc, 8, v149
	v_cmp_gt_u32_e64 s[26:27], 8, v158
	v_cmp_gt_u32_e64 s[36:37], 8, v159
	v_cmp_gt_u32_e64 s[38:39], 8, v160
	v_med3_i32 v165, v145, 0, 1
	v_med3_i32 v166, v146, 0, 1
	v_med3_i32 v167, v147, 0, 1
	v_med3_i32 v168, v148, 0, 1
	v_cndmask_b32_e64 v161, v161, v149, vcc
	v_cndmask_b32_e64 v162, v162, v158, s[26:27]
	v_cndmask_b32_e64 v163, v163, v159, s[36:37]
	v_cndmask_b32_e64 v164, v164, v160, s[38:39]
	v_lshl_add_u32 v161, v165, 4, v161
	v_lshl_add_u32 v162, v166, 4, v162
	v_lshl_add_u32 v163, v167, 4, v163
	v_lshl_add_u32 v164, v168, 4, v164
	v_lshl_add_u32 v165, v161, 5, v25
	v_lshl_add_u32 v166, v162, 5, v25
	v_lshl_add_u32 v167, v163, 5, v25
	v_lshl_add_u32 v168, v164, 5, v25
	ds_read_b32 v165, v165
	ds_read_b32 v166, v166
	ds_read_b32 v167, v167
	ds_read_b32 v168, v168
	s_waitcnt lgkmcnt(3)
	v_fma_mixlo_f16 v165, v88, s3, v165
	s_waitcnt lgkmcnt(2)
	v_fma_mixlo_f16 v166, v89, s3, v166
	s_waitcnt lgkmcnt(1)
	v_fma_mixlo_f16 v167, v90, s3, v167
	s_waitcnt lgkmcnt(0)
	v_fma_mixlo_f16 v168, v91, s3, v168
	ds_write_b16 v143, v165 offset:256
	ds_write_b16 v143, v166 offset:272
	ds_write_b16 v143, v167 offset:288
	ds_write_b16 v143, v168 offset:304
	s_mov_b64 exec, s[12:13]
	s_cmp_le_i32 s16, 2
	s_cbranch_scc1 .Lqk_done
	ds_read_b64 v[92:93], v142 offset:64
	s_cmp_gt_i32 s16, 8
	s_cbranch_scc0 .Lqk_n6_2
	v_add_lshl_u32 v115, s48, v115, 8
	v_add_u32_e32 v115, v144, v115
	global_load_dwordx4 v[72:75], v115, s[84:85]
	global_load_dwordx4 v[76:79], v115, s[84:85] offset:64
	global_load_dwordx4 v[80:83], v115, s[84:85] offset:128
	global_load_dwordx4 v[84:87], v115, s[84:85] offset:192
	s_waitcnt vmcnt(24)
	s_branch .Lqk_go_2
.Lqk_n6_2:
	s_cmp_gt_i32 s16, 7
	s_cbranch_scc0 .Lqk_n5_2
	s_waitcnt vmcnt(20)
	s_branch .Lqk_go_2
.Lqk_n5_2:
	s_cmp_gt_i32 s16, 6
	s_cbranch_scc0 .Lqk_n4_2
	s_waitcnt vmcnt(16)
	s_branch .Lqk_go_2
.Lqk_n4_2:
	s_cmp_gt_i32 s16, 5
	s_cbranch_scc0 .Lqk_n3_2
	s_waitcnt vmcnt(12)
	s_branch .Lqk_go_2
.Lqk_n3_2:
	s_cmp_gt_i32 s16, 4
	s_cbranch_scc0 .Lqk_n2_2
	s_waitcnt vmcnt(8)
	s_branch .Lqk_go_2

; __device__ __forceinline__ void dsa_unit(int wv, const Args& A, LAS unsigned char* lds, int s, int qt) {
;     ...
;         for (int kt = 0; kt < nt; ++kt) {
;             long k1[8];
;             DSA_LOADT(k1, kt + 1);
;             f32x4 a = {0.f, 0.f, 0.f, 0.f};
; #pragma unroll
;             for (int kk = 0; kk < 8; ++kk) a = __builtin_amdgcn_mfma_f32_16x16x32_fp8_fp8(kf[kk], qf[kk], a, 0, 0, 0);
;             if (fr < 8) {
; #pragma unroll
;                 for (int r = 0; r < 4; ++r) { const int e2 = kt * 16 + fq * 4 + r; const int key2 = lst[e2];
;                     Pw[e2 * 8 + fr] = (h16)(a[r] * 0.0625f + relb[rel_bucket(key2 - qpos) * 8 + fr]); } }
.Lqk_go_2:
	v_mfma_f32_16x16x32_fp8_fp8 v[88:91], v[124:125], v[34:35], 0
	v_mfma_f32_16x16x32_fp8_fp8 v[88:91], v[126:127], v[32:33], v[88:91]
	v_mfma_f32_16x16x32_fp8_fp8 v[88:91], v[128:129], v[38:39], v[88:91]
	v_mfma_f32_16x16x32_fp8_fp8 v[88:91], v[130:131], v[36:37], v[88:91]
	v_mfma_f32_16x16x32_fp8_fp8 v[88:91], v[132:133], v[42:43], v[88:91]
	v_mfma_f32_16x16x32_fp8_fp8 v[88:91], v[134:135], v[40:41], v[88:91]
	v_mfma_f32_16x16x32_fp8_fp8 v[88:91], v[136:137], v[46:47], v[88:91]
	v_mfma_f32_16x16x32_fp8_fp8 v[88:91], v[138:139], v[44:45], v[88:91]
	s_and_saveexec_b64 s[12:13], s[8:9]
	s_waitcnt lgkmcnt(0)
	v_and_b32_e32 v145, 0xffff, v92
	v_lshrrev_b32_e32 v146, 16, v92
	v_and_b32_e32 v147, 0xffff, v93
	v_lshrrev_b32_e32 v148, 16, v93
	v_subrev_u32_e32 v145, s1, v145
	v_subrev_u32_e32 v146, s1, v146
	v_subrev_u32_e32 v147, s1, v147
	v_subrev_u32_e32 v148, s1, v148
	v_sub_u32_e32 v149, 0, v145
	v_sub_u32_e32 v158, 0, v146
	v_sub_u32_e32 v159, 0, v147
	v_sub_u32_e32 v160, 0, v148
	v_max_i32_e32 v149, v145, v149
	v_max_i32_e32 v158, v146, v158
	v_max_i32_e32 v159, v147, v159
	v_max_i32_e32 v160, v148, v160
	v_mul_u32_u24_e32 v161, v149, v149
	v_mul_u32_u24_e32 v162, v158, v158
	v_mul_u32_u24_e32 v163, v159, v159
	v_mul_u32_u24_e32 v164, v160, v160
	v_cvt_f32_u32_e32 v161, v161
	v_cvt_f32_u32_e32 v162, v162
	v_cvt_f32_u32_e32 v163, v163
	v_cvt_f32_u32_e32 v164, v164
	v_lshrrev_b32_e32 v161, 23, v161
	v_lshrrev_b32_e32 v162, 23, v162
	v_lshrrev_b32_e32 v163, 23, v163
	v_lshrrev_b32_e32 v164, 23, v164
	v_add_u32_e32 v161, 0xffffff83, v161
	v_add_u32_e32 v162, 0xffffff83, v162
	v_add_u32_e32 v163, 0xffffff83, v163
	v_add_u32_e32 v164, 0xffffff83, v164
	v_min_u32_e32 v161, 15, v161
	v_min_u32_e32 v162, 15, v162
	v_min_u32_e32 v163, 15, v163
	v_min_u32_e32 v164, 15, v164
	v_cmp_gt_u32_e32 vcc, 8, v149
	v_cmp_gt_u32_e64 s[26:27], 8, v158
	v_cmp_gt_u32_e64 s[36:37], 8, v159
	v_cmp_gt_u32_e64 s[38:39], 8, v160
	v_med3_i32 v165, v145, 0, 1
	v_med3_i32 v166, v146, 0, 1
	v_med3_i32 v167, v147, 0, 1
	v_med3_i32 v168, v148, 0, 1
	v_cndmask_b32_e64 v161, v161, v149, vcc
	v_cndmask_b32_e64 v162, v162, v158, s[26:27]
	v_cndmask_b32_e64 v163, v163, v159, s[36:37]
	v_cndmask_b32_e64 v164, v164, v160, s[38:39]
	v_lshl_add_u32 v161, v165, 4, v161
	v_lshl_add_u32 v162, v166, 4, v162
	v_lshl_add_u32 v163, v167, 4, v163
	v_lshl_add_u32 v164, v168, 4, v164
	v_lshl_add_u32 v165, v161, 5, v25
	v_lshl_add_u32 v166, v162, 5, v25
	v_lshl_add_u32 v167, v163, 5, v25
	v_lshl_add_u32 v168, v164, 5, v25
	ds_read_b32 v165, v165
	ds_read_b32 v166, v166
	ds_read_b32 v167, v167
	ds_read_b32 v168, v168
	s_waitcnt lgkmcnt(3)
	v_fma_mixlo_f16 v165, v88, s3, v165
	s_waitcnt lgkmcnt(2)
	v_fma_mixlo_f16 v166, v89, s3, v166
	s_waitcnt lgkmcnt(1)
	v_fma_mixlo_f16 v167, v90, s3, v167
	s_waitcnt lgkmcnt(0)
	v_fma_mixlo_f16 v168, v91, s3, v168
	ds_write_b16 v143, v165 offset:512
	ds_write_b16 v143, v166 offset:528
	ds_write_b16 v143, v167 offset:544
	ds_write_b16 v143, v168 offset:560
	s_mov_b64 exec, s[12:13]
	s_cmp_le_i32 s16, 3
	s_cbranch_scc1 .Lqk_done
	ds_read_b64 v[92:93], v142 offset:96
	s_cmp_gt_i32 s16, 9
	s_cbranch_scc0 .Lqk_n6_3
	v_add_lshl_u32 v116, s48, v116, 8
	v_add_u32_e32 v116, v144, v116
	global_load_dwordx4 v[124:127], v116, s[84:85]
	global_load_dwordx4 v[128:131], v116, s[84:85] offset:64
	global_load_dwordx4 v[132:135], v116, s[84:85] offset:128
	global_load_dwordx4 v[136:139], v116, s[84:85] offset:192
	s_waitcnt vmcnt(24)
	s_branch .Lqk_go_3
.Lqk_n6_3:
	s_cmp_gt_i32 s16, 8
	s_cbranch_scc0 .Lqk_n5_3
	s_waitcnt vmcnt(20)
	s_branch .Lqk_go_3
.Lqk_n5_3:
	s_cmp_gt_i32 s16, 7
	s_cbranch_scc0 .Lqk_n4_3
	s_waitcnt vmcnt(16)
	s_branch .Lqk_go_3
.Lqk_n4_3:
	s_cmp_gt_i32 s16, 6
	s_cbranch_scc0 .Lqk_n3_3
	s_waitcnt vmcnt(12)
	s_branch .Lqk_go_3
.Lqk_n3_3:
	s_cmp_gt_i32 s16, 5
	s_cbranch_scc0 .Lqk_n2_3
	s_waitcnt vmcnt(8)
	s_branch .Lqk_go_3

; __device__ __forceinline__ void dsa_unit(int wv, const Args& A, LAS unsigned char* lds, int s, int qt) {
;     ...
;         for (int kt = 0; kt < nt; ++kt) {
;             long k1[8];
;             DSA_LOADT(k1, kt + 1);
;             f32x4 a = {0.f, 0.f, 0.f, 0.f};
; #pragma unroll
;             for (int kk = 0; kk < 8; ++kk) a = __builtin_amdgcn_mfma_f32_16x16x32_fp8_fp8(kf[kk], qf[kk], a, 0, 0, 0);
;             if (fr < 8) {
; #pragma unroll
;                 for (int r = 0; r < 4; ++r) { const int e2 = kt * 16 + fq * 4 + r; const int key2 = lst[e2];
;                     Pw[e2 * 8 + fr] = (h16)(a[r] * 0.0625f + relb[rel_bucket(key2 - qpos) * 8 + fr]); } }
.Lqk_go_3:
	v_mfma_f32_16x16x32_fp8_fp8 v[88:91], v[180:181], v[34:35], 0
	v_mfma_f32_16x16x32_fp8_fp8 v[88:91], v[182:183], v[32:33], v[88:91]
	v_mfma_f32_16x16x32_fp8_fp8 v[88:91], v[184:185], v[38:39], v[88:91]
	v_mfma_f32_16x16x32_fp8_fp8 v[88:91], v[186:187], v[36:37], v[88:91]
	v_mfma_f32_16x16x32_fp8_fp8 v[88:91], v[188:189], v[42:43], v[88:91]
	v_mfma_f32_16x16x32_fp8_fp8 v[88:91], v[190:191], v[40:41], v[88:91]
	v_mfma_f32_16x16x32_fp8_fp8 v[88:91], v[192:193], v[46:47], v[88:91]
	v_mfma_f32_16x16x32_fp8_fp8 v[88:91], v[194:195], v[44:45], v[88:91]
	s_and_saveexec_b64 s[12:13], s[8:9]
	s_waitcnt lgkmcnt(0)
	v_and_b32_e32 v145, 0xffff, v92
	v_lshrrev_b32_e32 v146, 16, v92
	v_and_b32_e32 v147, 0xffff, v93
	v_lshrrev_b32_e32 v148, 16, v93
	v_subrev_u32_e32 v145, s1, v145
	v_subrev_u32_e32 v146, s1, v146
	v_subrev_u32_e32 v147, s1, v147
	v_subrev_u32_e32 v148, s1, v148
	v_sub_u32_e32 v149, 0, v145
	v_sub_u32_e32 v158, 0, v146
	v_sub_u32_e32 v159, 0, v147
	v_sub_u32_e32 v160, 0, v148
	v_max_i32_e32 v149, v145, v149
	v_max_i32_e32 v158, v146, v158
	v_max_i32_e32 v159, v147, v159
	v_max_i32_e32 v160, v148, v160
	v_mul_u32_u24_e32 v161, v149, v149
	v_mul_u32_u24_e32 v162, v158, v158
	v_mul_u32_u24_e32 v163, v159, v159
	v_mul_u32_u24_e32 v164, v160, v160
	v_cvt_f32_u32_e32 v161, v161
	v_cvt_f32_u32_e32 v162, v162
	v_cvt_f32_u32_e32 v163, v163
	v_cvt_f32_u32_e32 v164, v164
	v_lshrrev_b32_e32 v161, 23, v161
	v_lshrrev_b32_e32 v162, 23, v162
	v_lshrrev_b32_e32 v163, 23, v163
	v_lshrrev_b32_e32 v164, 23, v164
	v_add_u32_e32 v161, 0xffffff83, v161
	v_add_u32_e32 v162, 0xffffff83, v162
	v_add_u32_e32 v163, 0xffffff83, v163
	v_add_u32_e32 v164, 0xffffff83, v164
	v_min_u32_e32 v161, 15, v161
	v_min_u32_e32 v162, 15, v162
	v_min_u32_e32 v163, 15, v163
	v_min_u32_e32 v164, 15, v164
	v_cmp_gt_u32_e32 vcc, 8, v149
	v_cmp_gt_u32_e64 s[26:27], 8, v158
	v_cmp_gt_u32_e64 s[36:37], 8, v159
	v_cmp_gt_u32_e64 s[38:39], 8, v160
	v_med3_i32 v165, v145, 0, 1
	v_med3_i32 v166, v146, 0, 1
	v_med3_i32 v167, v147, 0, 1
	v_med3_i32 v168, v148, 0, 1
	v_cndmask_b32_e64 v161, v161, v149, vcc
	v_cndmask_b32_e64 v162, v162, v158, s[26:27]
	v_cndmask_b32_e64 v163, v163, v159, s[36:37]
	v_cndmask_b32_e64 v164, v164, v160, s[38:39]
	v_lshl_add_u32 v161, v165, 4, v161
	v_lshl_add_u32 v162, v166, 4, v162
	v_lshl_add_u32 v163, v167, 4, v163
	v_lshl_add_u32 v164, v168, 4, v164
	v_lshl_add_u32 v165, v161, 5, v25
	v_lshl_add_u32 v166, v162, 5, v25
	v_lshl_add_u32 v167, v163, 5, v25
	v_lshl_add_u32 v168, v164, 5, v25
	ds_read_b32 v165, v165
	ds_read_b32 v166, v166
	ds_read_b32 v167, v167
	ds_read_b32 v168, v168
	s_waitcnt lgkmcnt(3)
	v_fma_mixlo_f16 v165, v88, s3, v165
	s_waitcnt lgkmcnt(2)
	v_fma_mixlo_f16 v166, v89, s3, v166
	s_waitcnt lgkmcnt(1)
	v_fma_mixlo_f16 v167, v90, s3, v167
	s_waitcnt lgkmcnt(0)
	v_fma_mixlo_f16 v168, v91, s3, v168
	ds_write_b16 v143, v165 offset:768
	ds_write_b16 v143, v166 offset:784
	ds_write_b16 v143, v167 offset:800
	ds_write_b16 v143, v168 offset:816
	s_mov_b64 exec, s[12:13]
	s_cmp_le_i32 s16, 4
	s_cbranch_scc1 .Lqk_done
	ds_read_b64 v[92:93], v142 offset:128
	s_cmp_gt_i32 s16, 10
	s_cbranch_scc0 .Lqk_n6_4
	v_add_lshl_u32 v117, s48, v117, 8
	v_add_u32_e32 v117, v144, v117
	global_load_dwordx4 v[180:183], v117, s[84:85]
	global_load_dwordx4 v[184:187], v117, s[84:85] offset:64
	global_load_dwordx4 v[188:191], v117, s[84:85] offset:128
	global_load_dwordx4 v[192:195], v117, s[84:85] offset:192
	s_waitcnt vmcnt(24)
	s_branch .Lqk_go_4
.Lqk_n6_4:
	s_cmp_gt_i32 s16, 9
	s_cbranch_scc0 .Lqk_n5_4
	s_waitcnt vmcnt(20)
	s_branch .Lqk_go_4
.Lqk_n5_4:
	s_cmp_gt_i32 s16, 8
	s_cbranch_scc0 .Lqk_n4_4
	s_waitcnt vmcnt(16)
	s_branch .Lqk_go_4
.Lqk_n4_4:
	s_cmp_gt_i32 s16, 7
	s_cbranch_scc0 .Lqk_n3_4
	s_waitcnt vmcnt(12)
	s_branch .Lqk_go_4
.Lqk_n3_4:
	s_cmp_gt_i32 s16, 6
	s_cbranch_scc0 .Lqk_n2_4
	s_waitcnt vmcnt(8)
	s_branch .Lqk_go_4

; __device__ __forceinline__ void dsa_unit(int wv, const Args& A, LAS unsigned char* lds, int s, int qt) {
;     ...
;         for (int kt = 0; kt < nt; ++kt) {
;             long k1[8];
;             DSA_LOADT(k1, kt + 1);
;             f32x4 a = {0.f, 0.f, 0.f, 0.f};
; #pragma unroll
;             for (int kk = 0; kk < 8; ++kk) a = __builtin_amdgcn_mfma_f32_16x16x32_fp8_fp8(kf[kk], qf[kk], a, 0, 0, 0);
;             if (fr < 8) {
; #pragma unroll
;                 for (int r = 0; r < 4; ++r) { const int e2 = kt * 16 + fq * 4 + r; const int key2 = lst[e2];
;                     Pw[e2 * 8 + fr] = (h16)(a[r] * 0.0625f + relb[rel_bucket(key2 - qpos) * 8 + fr]); } }
.Lqk_go_4:
	v_mfma_f32_16x16x32_fp8_fp8 v[88:91], v[196:197], v[34:35], 0
	v_mfma_f32_16x16x32_fp8_fp8 v[88:91], v[198:199], v[32:33], v[88:91]
	v_mfma_f32_16x16x32_fp8_fp8 v[88:91], v[200:201], v[38:39], v[88:91]
	v_mfma_f32_16x16x32_fp8_fp8 v[88:91], v[202:203], v[36:37], v[88:91]
	v_mfma_f32_16x16x32_fp8_fp8 v[88:91], v[204:205], v[42:43], v[88:91]
	v_mfma_f32_16x16x32_fp8_fp8 v[88:91], v[206:207], v[40:41], v[88:91]
	v_mfma_f32_16x16x32_fp8_fp8 v[88:91], v[208:209], v[46:47], v[88:91]
	v_mfma_f32_16x16x32_fp8_fp8 v[88:91], v[210:211], v[44:45], v[88:91]
	s_and_saveexec_b64 s[12:13], s[8:9]
	s_waitcnt lgkmcnt(0)
	v_and_b32_e32 v145, 0xffff, v92
	v_lshrrev_b32_e32 v146, 16, v92
	v_and_b32_e32 v147, 0xffff, v93
	v_lshrrev_b32_e32 v148, 16, v93
	v_subrev_u32_e32 v145, s1, v145
	v_subrev_u32_e32 v146, s1, v146
	v_subrev_u32_e32 v147, s1, v147
	v_subrev_u32_e32 v148, s1, v148
	v_sub_u32_e32 v149, 0, v145
	v_sub_u32_e32 v158, 0, v146
	v_sub_u32_e32 v159, 0, v147
	v_sub_u32_e32 v160, 0, v148
	v_max_i32_e32 v149, v145, v149
	v_max_i32_e32 v158, v146, v158
	v_max_i32_e32 v159, v147, v159
	v_max_i32_e32 v160, v148, v160
	v_mul_u32_u24_e32 v161, v149, v149
	v_mul_u32_u24_e32 v162, v158, v158
	v_mul_u32_u24_e32 v163, v159, v159
	v_mul_u32_u24_e32 v164, v160, v160
	v_cvt_f32_u32_e32 v161, v161
	v_cvt_f32_u32_e32 v162, v162
	v_cvt_f32_u32_e32 v163, v163
	v_cvt_f32_u32_e32 v164, v164
	v_lshrrev_b32_e32 v161, 23, v161
	v_lshrrev_b32_e32 v162, 23, v162
	v_lshrrev_b32_e32 v163, 23, v163
	v_lshrrev_b32_e32 v164, 23, v164
	v_add_u32_e32 v161, 0xffffff83, v161
	v_add_u32_e32 v162, 0xffffff83, v162
	v_add_u32_e32 v163, 0xffffff83, v163
	v_add_u32_e32 v164, 0xffffff83, v164
	v_min_u32_e32 v161, 15, v161
	v_min_u32_e32 v162, 15, v162
	v_min_u32_e32 v163, 15, v163
	v_min_u32_e32 v164, 15, v164
	v_cmp_gt_u32_e32 vcc, 8, v149
	v_cmp_gt_u32_e64 s[26:27], 8, v158
	v_cmp_gt_u32_e64 s[36:37], 8, v159
	v_cmp_gt_u32_e64 s[38:39], 8, v160
	v_med3_i32 v165, v145, 0, 1
	v_med3_i32 v166, v146, 0, 1
	v_med3_i32 v167, v147, 0, 1
	v_med3_i32 v168, v148, 0, 1
	v_cndmask_b32_e64 v161, v161, v149, vcc
	v_cndmask_b32_e64 v162, v162, v158, s[26:27]
	v_cndmask_b32_e64 v163, v163, v159, s[36:37]
	v_cndmask_b32_e64 v164, v164, v160, s[38:39]
	v_lshl_add_u32 v161, v165, 4, v161
	v_lshl_add_u32 v162, v166, 4, v162
	v_lshl_add_u32 v163, v167, 4, v163
	v_lshl_add_u32 v164, v168, 4, v164
	v_lshl_add_u32 v165, v161, 5, v25
	v_lshl_add_u32 v166, v162, 5, v25
	v_lshl_add_u32 v167, v163, 5, v25
	v_lshl_add_u32 v168, v164, 5, v25
	ds_read_b32 v165, v165
	ds_read_b32 v166, v166
	ds_read_b32 v167, v167
	ds_read_b32 v168, v168
	s_waitcnt lgkmcnt(3)
	v_fma_mixlo_f16 v165, v88, s3, v165
	s_waitcnt lgkmcnt(2)
	v_fma_mixlo_f16 v166, v89, s3, v166
	s_waitcnt lgkmcnt(1)
	v_fma_mixlo_f16 v167, v90, s3, v167
	s_waitcnt lgkmcnt(0)
	v_fma_mixlo_f16 v168, v91, s3, v168
	ds_write_b16 v143, v165 offset:1024
	ds_write_b16 v143, v166 offset:1040
	ds_write_b16 v143, v167 offset:1056
	ds_write_b16 v143, v168 offset:1072
	s_mov_b64 exec, s[12:13]
	s_cmp_le_i32 s16, 5
	s_cbranch_scc1 .Lqk_done
	ds_read_b64 v[92:93], v142 offset:160
	s_cmp_gt_i32 s16, 11
	s_cbranch_scc0 .Lqk_n6_5
	v_add_lshl_u32 v118, s48, v118, 8
	v_add_u32_e32 v118, v144, v118
	global_load_dwordx4 v[196:199], v118, s[84:85]
	global_load_dwordx4 v[200:203], v118, s[84:85] offset:64
	global_load_dwordx4 v[204:207], v118, s[84:85] offset:128
	global_load_dwordx4 v[208:211], v118, s[84:85] offset:192
	s_waitcnt vmcnt(24)
	s_branch .Lqk_go_5
.Lqk_n6_5:
	s_cmp_gt_i32 s16, 10
	s_cbranch_scc0 .Lqk_n5_5
	s_waitcnt vmcnt(20)
	s_branch .Lqk_go_5
.Lqk_n5_5:
	s_cmp_gt_i32 s16, 9
	s_cbranch_scc0 .Lqk_n4_5
	s_waitcnt vmcnt(16)
	s_branch .Lqk_go_5
.Lqk_n4_5:
	s_cmp_gt_i32 s16, 8
	s_cbranch_scc0 .Lqk_n3_5
	s_waitcnt vmcnt(12)
	s_branch .Lqk_go_5
.Lqk_n3_5:
	s_cmp_gt_i32 s16, 7
	s_cbranch_scc0 .Lqk_n2_5
	s_waitcnt vmcnt(8)
	s_branch .Lqk_go_5

; __device__ __forceinline__ void dsa_unit(int wv, const Args& A, LAS unsigned char* lds, int s, int qt) {
;     ...
;         for (int kt = 0; kt < nt; ++kt) {
;             long k1[8];
;             DSA_LOADT(k1, kt + 1);
;             f32x4 a = {0.f, 0.f, 0.f, 0.f};
; #pragma unroll
;             for (int kk = 0; kk < 8; ++kk) a = __builtin_amdgcn_mfma_f32_16x16x32_fp8_fp8(kf[kk], qf[kk], a, 0, 0, 0);
;             if (fr < 8) {
; #pragma unroll
;                 for (int r = 0; r < 4; ++r) { const int e2 = kt * 16 + fq * 4 + r; const int key2 = lst[e2];
;                     Pw[e2 * 8 + fr] = (h16)(a[r] * 0.0625f + relb[rel_bucket(key2 - qpos) * 8 + fr]); } }
.Lqk_go_5:
	v_mfma_f32_16x16x32_fp8_fp8 v[88:91], v[212:213], v[34:35], 0
	v_mfma_f32_16x16x32_fp8_fp8 v[88:91], v[214:215], v[32:33], v[88:91]
	v_mfma_f32_16x16x32_fp8_fp8 v[88:91], v[216:217], v[38:39], v[88:91]
	v_mfma_f32_16x16x32_fp8_fp8 v[88:91], v[218:219], v[36:37], v[88:91]
	v_mfma_f32_16x16x32_fp8_fp8 v[88:91], v[220:221], v[42:43], v[88:91]
	v_mfma_f32_16x16x32_fp8_fp8 v[88:91], v[222:223], v[40:41], v[88:91]
	v_mfma_f32_16x16x32_fp8_fp8 v[88:91], v[224:225], v[46:47], v[88:91]
	v_mfma_f32_16x16x32_fp8_fp8 v[88:91], v[226:227], v[44:45], v[88:91]
	s_and_saveexec_b64 s[12:13], s[8:9]
	s_waitcnt lgkmcnt(0)
	v_and_b32_e32 v145, 0xffff, v92
	v_lshrrev_b32_e32 v146, 16, v92
	v_and_b32_e32 v147, 0xffff, v93
	v_lshrrev_b32_e32 v148, 16, v93
	v_subrev_u32_e32 v145, s1, v145
	v_subrev_u32_e32 v146, s1, v146
	v_subrev_u32_e32 v147, s1, v147
	v_subrev_u32_e32 v148, s1, v148
	v_sub_u32_e32 v149, 0, v145
	v_sub_u32_e32 v158, 0, v146
	v_sub_u32_e32 v159, 0, v147
	v_sub_u32_e32 v160, 0, v148
	v_max_i32_e32 v149, v145, v149
	v_max_i32_e32 v158, v146, v158
	v_max_i32_e32 v159, v147, v159
	v_max_i32_e32 v160, v148, v160
	v_mul_u32_u24_e32 v161, v149, v149
	v_mul_u32_u24_e32 v162, v158, v158
	v_mul_u32_u24_e32 v163, v159, v159
	v_mul_u32_u24_e32 v164, v160, v160
	v_cvt_f32_u32_e32 v161, v161
	v_cvt_f32_u32_e32 v162, v162
	v_cvt_f32_u32_e32 v163, v163
	v_cvt_f32_u32_e32 v164, v164
	v_lshrrev_b32_e32 v161, 23, v161
	v_lshrrev_b32_e32 v162, 23, v162
	v_lshrrev_b32_e32 v163, 23, v163
	v_lshrrev_b32_e32 v164, 23, v164
	v_add_u32_e32 v161, 0xffffff83, v161
	v_add_u32_e32 v162, 0xffffff83, v162
	v_add_u32_e32 v163, 0xffffff83, v163
	v_add_u32_e32 v164, 0xffffff83, v164
	v_min_u32_e32 v161, 15, v161
	v_min_u32_e32 v162, 15, v162
	v_min_u32_e32 v163, 15, v163
	v_min_u32_e32 v164, 15, v164
	v_cmp_gt_u32_e32 vcc, 8, v149
	v_cmp_gt_u32_e64 s[26:27], 8, v158
	v_cmp_gt_u32_e64 s[36:37], 8, v159
	v_cmp_gt_u32_e64 s[38:39], 8, v160
	v_med3_i32 v165, v145, 0, 1
	v_med3_i32 v166, v146, 0, 1
	v_med3_i32 v167, v147, 0, 1
	v_med3_i32 v168, v148, 0, 1
	v_cndmask_b32_e64 v161, v161, v149, vcc
	v_cndmask_b32_e64 v162, v162, v158, s[26:27]
	v_cndmask_b32_e64 v163, v163, v159, s[36:37]
	v_cndmask_b32_e64 v164, v164, v160, s[38:39]
	v_lshl_add_u32 v161, v165, 4, v161
	v_lshl_add_u32 v162, v166, 4, v162
	v_lshl_add_u32 v163, v167, 4, v163
	v_lshl_add_u32 v164, v168, 4, v164
	v_lshl_add_u32 v165, v161, 5, v25
	v_lshl_add_u32 v166, v162, 5, v25
	v_lshl_add_u32 v167, v163, 5, v25
	v_lshl_add_u32 v168, v164, 5, v25
	ds_read_b32 v165, v165
	ds_read_b32 v166, v166
	ds_read_b32 v167, v167
	ds_read_b32 v168, v168
	s_waitcnt lgkmcnt(3)
	v_fma_mixlo_f16 v165, v88, s3, v165
	s_waitcnt lgkmcnt(2)
	v_fma_mixlo_f16 v166, v89, s3, v166
	s_waitcnt lgkmcnt(1)
	v_fma_mixlo_f16 v167, v90, s3, v167
	s_waitcnt lgkmcnt(0)
	v_fma_mixlo_f16 v168, v91, s3, v168
	ds_write_b16 v143, v165 offset:1280
	ds_write_b16 v143, v166 offset:1296
	ds_write_b16 v143, v167 offset:1312
	ds_write_b16 v143, v168 offset:1328
	s_mov_b64 exec, s[12:13]
	s_cmp_le_i32 s16, 6
	s_cbranch_scc1 .Lqk_done
	ds_read_b64 v[92:93], v142 offset:192
	s_cmp_gt_i32 s16, 12
	s_cbranch_scc0 .Lqk_n6_6
	v_add_lshl_u32 v119, s48, v119, 8
	v_add_u32_e32 v119, v144, v119
	global_load_dwordx4 v[212:215], v119, s[84:85]
	global_load_dwordx4 v[216:219], v119, s[84:85] offset:64
	global_load_dwordx4 v[220:223], v119, s[84:85] offset:128
	global_load_dwordx4 v[224:227], v119, s[84:85] offset:192
	s_waitcnt vmcnt(24)
	s_branch .Lqk_go_6
.Lqk_n6_6:
	s_cmp_gt_i32 s16, 11
	s_cbranch_scc0 .Lqk_n5_6
	s_waitcnt vmcnt(20)
	s_branch .Lqk_go_6
.Lqk_n5_6:
	s_cmp_gt_i32 s16, 10
	s_cbranch_scc0 .Lqk_n4_6
	s_waitcnt vmcnt(16)
	s_branch .Lqk_go_6
.Lqk_n4_6:
	s_cmp_gt_i32 s16, 9
	s_cbranch_scc0 .Lqk_n3_6
	s_waitcnt vmcnt(12)
	s_branch .Lqk_go_6
.Lqk_n3_6:
	s_cmp_gt_i32 s16, 8
	s_cbranch_scc0 .Lqk_n2_6
	s_waitcnt vmcnt(8)
	s_branch .Lqk_go_6

; __device__ __forceinline__ void dsa_unit(int wv, const Args& A, LAS unsigned char* lds, int s, int qt) {
;     ...
;         for (int kt = 0; kt < nt; ++kt) {
;             long k1[8];
;             DSA_LOADT(k1, kt + 1);
;             f32x4 a = {0.f, 0.f, 0.f, 0.f};
; #pragma unroll
;             for (int kk = 0; kk < 8; ++kk) a = __builtin_amdgcn_mfma_f32_16x16x32_fp8_fp8(kf[kk], qf[kk], a, 0, 0, 0);
;             if (fr < 8) {
; #pragma unroll
;                 for (int r = 0; r < 4; ++r) { const int e2 = kt * 16 + fq * 4 + r; const int key2 = lst[e2];
;                     Pw[e2 * 8 + fr] = (h16)(a[r] * 0.0625f + relb[rel_bucket(key2 - qpos) * 8 + fr]); } }
.Lqk_go_6:
	v_mfma_f32_16x16x32_fp8_fp8 v[88:91], v[240:241], v[34:35], 0
	v_mfma_f32_16x16x32_fp8_fp8 v[88:91], v[242:243], v[32:33], v[88:91]
	v_mfma_f32_16x16x32_fp8_fp8 v[88:91], v[244:245], v[38:39], v[88:91]
	v_mfma_f32_16x16x32_fp8_fp8 v[88:91], v[246:247], v[36:37], v[88:91]
	v_mfma_f32_16x16x32_fp8_fp8 v[88:91], v[248:249], v[42:43], v[88:91]
	v_mfma_f32_16x16x32_fp8_fp8 v[88:91], v[250:251], v[40:41], v[88:91]
	v_mfma_f32_16x16x32_fp8_fp8 v[88:91], v[252:253], v[46:47], v[88:91]
	v_mfma_f32_16x16x32_fp8_fp8 v[88:91], v[254:255], v[44:45], v[88:91]
	s_and_saveexec_b64 s[12:13], s[8:9]
	s_waitcnt lgkmcnt(0)
	v_and_b32_e32 v145, 0xffff, v92
	v_lshrrev_b32_e32 v146, 16, v92
	v_and_b32_e32 v147, 0xffff, v93
	v_lshrrev_b32_e32 v148, 16, v93
	v_subrev_u32_e32 v145, s1, v145
	v_subrev_u32_e32 v146, s1, v146
	v_subrev_u32_e32 v147, s1, v147
	v_subrev_u32_e32 v148, s1, v148
	v_sub_u32_e32 v149, 0, v145
	v_sub_u32_e32 v158, 0, v146
	v_sub_u32_e32 v159, 0, v147
	v_sub_u32_e32 v160, 0, v148
	v_max_i32_e32 v149, v145, v149
	v_max_i32_e32 v158, v146, v158
	v_max_i32_e32 v159, v147, v159
	v_max_i32_e32 v160, v148, v160
	v_mul_u32_u24_e32 v161, v149, v149
	v_mul_u32_u24_e32 v162, v158, v158
	v_mul_u32_u24_e32 v163, v159, v159
	v_mul_u32_u24_e32 v164, v160, v160
	v_cvt_f32_u32_e32 v161, v161
	v_cvt_f32_u32_e32 v162, v162
	v_cvt_f32_u32_e32 v163, v163
	v_cvt_f32_u32_e32 v164, v164
	v_lshrrev_b32_e32 v161, 23, v161
	v_lshrrev_b32_e32 v162, 23, v162
	v_lshrrev_b32_e32 v163, 23, v163
	v_lshrrev_b32_e32 v164, 23, v164
	v_add_u32_e32 v161, 0xffffff83, v161
	v_add_u32_e32 v162, 0xffffff83, v162
	v_add_u32_e32 v163, 0xffffff83, v163
	v_add_u32_e32 v164, 0xffffff83, v164
	v_min_u32_e32 v161, 15, v161
	v_min_u32_e32 v162, 15, v162
	v_min_u32_e32 v163, 15, v163
	v_min_u32_e32 v164, 15, v164
	v_cmp_gt_u32_e32 vcc, 8, v149
	v_cmp_gt_u32_e64 s[26:27], 8, v158
	v_cmp_gt_u32_e64 s[36:37], 8, v159
	v_cmp_gt_u32_e64 s[38:39], 8, v160
	v_med3_i32 v165, v145, 0, 1
	v_med3_i32 v166, v146, 0, 1
	v_med3_i32 v167, v147, 0, 1
	v_med3_i32 v168, v148, 0, 1
	v_cndmask_b32_e64 v161, v161, v149, vcc
	v_cndmask_b32_e64 v162, v162, v158, s[26:27]
	v_cndmask_b32_e64 v163, v163, v159, s[36:37]
	v_cndmask_b32_e64 v164, v164, v160, s[38:39]
	v_lshl_add_u32 v161, v165, 4, v161
	v_lshl_add_u32 v162, v166, 4, v162
	v_lshl_add_u32 v163, v167, 4, v163
	v_lshl_add_u32 v164, v168, 4, v164
	v_lshl_add_u32 v165, v161, 5, v25
	v_lshl_add_u32 v166, v162, 5, v25
	v_lshl_add_u32 v167, v163, 5, v25
	v_lshl_add_u32 v168, v164, 5, v25
	ds_read_b32 v165, v165
	ds_read_b32 v166, v166
	ds_read_b32 v167, v167
	ds_read_b32 v168, v168
	s_waitcnt lgkmcnt(3)
	v_fma_mixlo_f16 v165, v88, s3, v165
	s_waitcnt lgkmcnt(2)
	v_fma_mixlo_f16 v166, v89, s3, v166
	s_waitcnt lgkmcnt(1)
	v_fma_mixlo_f16 v167, v90, s3, v167
	s_waitcnt lgkmcnt(0)
	v_fma_mixlo_f16 v168, v91, s3, v168
	ds_write_b16 v143, v165 offset:1536
	ds_write_b16 v143, v166 offset:1552
	ds_write_b16 v143, v167 offset:1568
	ds_write_b16 v143, v168 offset:1584
	s_mov_b64 exec, s[12:13]
	s_cmp_le_i32 s16, 7
	s_cbranch_scc1 .Lqk_done
	ds_read_b64 v[92:93], v142 offset:224
	s_cmp_gt_i32 s16, 13
	s_cbranch_scc0 .Lqk_n6_7
	v_add_lshl_u32 v120, s48, v120, 8
	v_add_u32_e32 v120, v144, v120
	global_load_dwordx4 v[240:243], v120, s[84:85]
	global_load_dwordx4 v[244:247], v120, s[84:85] offset:64
	global_load_dwordx4 v[248:251], v120, s[84:85] offset:128
	global_load_dwordx4 v[252:255], v120, s[84:85] offset:192
	s_waitcnt vmcnt(24)
	s_branch .Lqk_go_7
.Lqk_n6_7:
	s_cmp_gt_i32 s16, 12
	s_cbranch_scc0 .Lqk_n5_7
	s_waitcnt vmcnt(20)
	s_branch .Lqk_go_7
.Lqk_n5_7:
	s_cmp_gt_i32 s16, 11
	s_cbranch_scc0 .Lqk_n4_7
	s_waitcnt vmcnt(16)
	s_branch .Lqk_go_7
.Lqk_n4_7:
	s_cmp_gt_i32 s16, 10
	s_cbranch_scc0 .Lqk_n3_7
	s_waitcnt vmcnt(12)
	s_branch .Lqk_go_7
.Lqk_n3_7:
	s_cmp_gt_i32 s16, 9
	s_cbranch_scc0 .Lqk_n2_7
	s_waitcnt vmcnt(8)
	s_branch .Lqk_go_7

; __device__ __forceinline__ void dsa_unit(int wv, const Args& A, LAS unsigned char* lds, int s, int qt) {
;     ...
;         for (int kt = 0; kt < nt; ++kt) {
;             long k1[8];
;             DSA_LOADT(k1, kt + 1);
;             f32x4 a = {0.f, 0.f, 0.f, 0.f};
; #pragma unroll
;             for (int kk = 0; kk < 8; ++kk) a = __builtin_amdgcn_mfma_f32_16x16x32_fp8_fp8(kf[kk], qf[kk], a, 0, 0, 0);
;             if (fr < 8) {
; #pragma unroll
;                 for (int r = 0; r < 4; ++r) { const int e2 = kt * 16 + fq * 4 + r; const int key2 = lst[e2];
;                     Pw[e2 * 8 + fr] = (h16)(a[r] * 0.0625f + relb[rel_bucket(key2 - qpos) * 8 + fr]); } }
.Lqk_go_7:
	v_mfma_f32_16x16x32_fp8_fp8 v[88:91], v[56:57], v[34:35], 0
	v_mfma_f32_16x16x32_fp8_fp8 v[88:91], v[58:59], v[32:33], v[88:91]
	v_mfma_f32_16x16x32_fp8_fp8 v[88:91], v[60:61], v[38:39], v[88:91]
	v_mfma_f32_16x16x32_fp8_fp8 v[88:91], v[62:63], v[36:37], v[88:91]
	v_mfma_f32_16x16x32_fp8_fp8 v[88:91], v[64:65], v[42:43], v[88:91]
	v_mfma_f32_16x16x32_fp8_fp8 v[88:91], v[66:67], v[40:41], v[88:91]
	v_mfma_f32_16x16x32_fp8_fp8 v[88:91], v[68:69], v[46:47], v[88:91]
	v_mfma_f32_16x16x32_fp8_fp8 v[88:91], v[70:71], v[44:45], v[88:91]
	s_and_saveexec_b64 s[12:13], s[8:9]
	s_waitcnt lgkmcnt(0)
	v_and_b32_e32 v145, 0xffff, v92
	v_lshrrev_b32_e32 v146, 16, v92
	v_and_b32_e32 v147, 0xffff, v93
	v_lshrrev_b32_e32 v148, 16, v93
	v_subrev_u32_e32 v145, s1, v145
	v_subrev_u32_e32 v146, s1, v146
	v_subrev_u32_e32 v147, s1, v147
	v_subrev_u32_e32 v148, s1, v148
	v_sub_u32_e32 v149, 0, v145
	v_sub_u32_e32 v158, 0, v146
	v_sub_u32_e32 v159, 0, v147
	v_sub_u32_e32 v160, 0, v148
	v_max_i32_e32 v149, v145, v149
	v_max_i32_e32 v158, v146, v158
	v_max_i32_e32 v159, v147, v159
	v_max_i32_e32 v160, v148, v160
	v_mul_u32_u24_e32 v161, v149, v149
	v_mul_u32_u24_e32 v162, v158, v158
	v_mul_u32_u24_e32 v163, v159, v159
	v_mul_u32_u24_e32 v164, v160, v160
	v_cvt_f32_u32_e32 v161, v161
	v_cvt_f32_u32_e32 v162, v162
	v_cvt_f32_u32_e32 v163, v163
	v_cvt_f32_u32_e32 v164, v164
	v_lshrrev_b32_e32 v161, 23, v161
	v_lshrrev_b32_e32 v162, 23, v162
	v_lshrrev_b32_e32 v163, 23, v163
	v_lshrrev_b32_e32 v164, 23, v164
	v_add_u32_e32 v161, 0xffffff83, v161
	v_add_u32_e32 v162, 0xffffff83, v162
	v_add_u32_e32 v163, 0xffffff83, v163
	v_add_u32_e32 v164, 0xffffff83, v164
	v_min_u32_e32 v161, 15, v161
	v_min_u32_e32 v162, 15, v162
	v_min_u32_e32 v163, 15, v163
	v_min_u32_e32 v164, 15, v164
	v_cmp_gt_u32_e32 vcc, 8, v149
	v_cmp_gt_u32_e64 s[26:27], 8, v158
	v_cmp_gt_u32_e64 s[36:37], 8, v159
	v_cmp_gt_u32_e64 s[38:39], 8, v160
	v_med3_i32 v165, v145, 0, 1
	v_med3_i32 v166, v146, 0, 1
	v_med3_i32 v167, v147, 0, 1
	v_med3_i32 v168, v148, 0, 1
	v_cndmask_b32_e64 v161, v161, v149, vcc
	v_cndmask_b32_e64 v162, v162, v158, s[26:27]
	v_cndmask_b32_e64 v163, v163, v159, s[36:37]
	v_cndmask_b32_e64 v164, v164, v160, s[38:39]
	v_lshl_add_u32 v161, v165, 4, v161
	v_lshl_add_u32 v162, v166, 4, v162
	v_lshl_add_u32 v163, v167, 4, v163
	v_lshl_add_u32 v164, v168, 4, v164
	v_lshl_add_u32 v165, v161, 5, v25
	v_lshl_add_u32 v166, v162, 5, v25
	v_lshl_add_u32 v167, v163, 5, v25
	v_lshl_add_u32 v168, v164, 5, v25
	ds_read_b32 v165, v165
	ds_read_b32 v166, v166
	ds_read_b32 v167, v167
	ds_read_b32 v168, v168
	s_waitcnt lgkmcnt(3)
	v_fma_mixlo_f16 v165, v88, s3, v165
	s_waitcnt lgkmcnt(2)
	v_fma_mixlo_f16 v166, v89, s3, v166
	s_waitcnt lgkmcnt(1)
	v_fma_mixlo_f16 v167, v90, s3, v167
	s_waitcnt lgkmcnt(0)
	v_fma_mixlo_f16 v168, v91, s3, v168
	ds_write_b16 v143, v165 offset:1792
	ds_write_b16 v143, v166 offset:1808
	ds_write_b16 v143, v167 offset:1824
	ds_write_b16 v143, v168 offset:1840
	s_mov_b64 exec, s[12:13]
	s_cmp_le_i32 s16, 8
	s_cbranch_scc1 .Lqk_done
	ds_read_b64 v[92:93], v142 offset:256
	s_cmp_gt_i32 s16, 14
	s_cbranch_scc0 .Lqk_n6_8
	v_add_lshl_u32 v121, s48, v121, 8
	v_add_u32_e32 v121, v144, v121
	global_load_dwordx4 v[56:59], v121, s[84:85]
	global_load_dwordx4 v[60:63], v121, s[84:85] offset:64
	global_load_dwordx4 v[64:67], v121, s[84:85] offset:128
	global_load_dwordx4 v[68:71], v121, s[84:85] offset:192
	s_waitcnt vmcnt(24)
	s_branch .Lqk_go_8
.Lqk_n6_8:
	s_cmp_gt_i32 s16, 13
	s_cbranch_scc0 .Lqk_n5_8
	s_waitcnt vmcnt(20)
	s_branch .Lqk_go_8
.Lqk_n5_8:
	s_cmp_gt_i32 s16, 12
	s_cbranch_scc0 .Lqk_n4_8
	s_waitcnt vmcnt(16)
	s_branch .Lqk_go_8
.Lqk_n4_8:
	s_cmp_gt_i32 s16, 11
	s_cbranch_scc0 .Lqk_n3_8
	s_waitcnt vmcnt(12)
	s_branch .Lqk_go_8
.Lqk_n3_8:
	s_cmp_gt_i32 s16, 10
	s_cbranch_scc0 .Lqk_n2_8
	s_waitcnt vmcnt(8)
	s_branch .Lqk_go_8

; __device__ __forceinline__ void dsa_unit(int wv, const Args& A, LAS unsigned char* lds, int s, int qt) {
;     ...
;         for (int kt = 0; kt < nt; ++kt) {
;             long k1[8];
;             DSA_LOADT(k1, kt + 1);
;             f32x4 a = {0.f, 0.f, 0.f, 0.f};
; #pragma unroll
;             for (int kk = 0; kk < 8; ++kk) a = __builtin_amdgcn_mfma_f32_16x16x32_fp8_fp8(kf[kk], qf[kk], a, 0, 0, 0);
;             if (fr < 8) {
; #pragma unroll
;                 for (int r = 0; r < 4; ++r) { const int e2 = kt * 16 + fq * 4 + r; const int key2 = lst[e2];
;                     Pw[e2 * 8 + fr] = (h16)(a[r] * 0.0625f + relb[rel_bucket(key2 - qpos) * 8 + fr]); } }
.Lqk_go_8:
	v_mfma_f32_16x16x32_fp8_fp8 v[88:91], v[72:73], v[34:35], 0
	v_mfma_f32_16x16x32_fp8_fp8 v[88:91], v[74:75], v[32:33], v[88:91]
	v_mfma_f32_16x16x32_fp8_fp8 v[88:91], v[76:77], v[38:39], v[88:91]
	v_mfma_f32_16x16x32_fp8_fp8 v[88:91], v[78:79], v[36:37], v[88:91]
	v_mfma_f32_16x16x32_fp8_fp8 v[88:91], v[80:81], v[42:43], v[88:91]
	v_mfma_f32_16x16x32_fp8_fp8 v[88:91], v[82:83], v[40:41], v[88:91]
	v_mfma_f32_16x16x32_fp8_fp8 v[88:91], v[84:85], v[46:47], v[88:91]
	v_mfma_f32_16x16x32_fp8_fp8 v[88:91], v[86:87], v[44:45], v[88:91]
	s_and_saveexec_b64 s[12:13], s[8:9]
	s_waitcnt lgkmcnt(0)
	v_and_b32_e32 v145, 0xffff, v92
	v_lshrrev_b32_e32 v146, 16, v92
	v_and_b32_e32 v147, 0xffff, v93
	v_lshrrev_b32_e32 v148, 16, v93
	v_subrev_u32_e32 v145, s1, v145
	v_subrev_u32_e32 v146, s1, v146
	v_subrev_u32_e32 v147, s1, v147
	v_subrev_u32_e32 v148, s1, v148
	v_sub_u32_e32 v149, 0, v145
	v_sub_u32_e32 v158, 0, v146
	v_sub_u32_e32 v159, 0, v147
	v_sub_u32_e32 v160, 0, v148
	v_max_i32_e32 v149, v145, v149
	v_max_i32_e32 v158, v146, v158
	v_max_i32_e32 v159, v147, v159
	v_max_i32_e32 v160, v148, v160
	v_mul_u32_u24_e32 v161, v149, v149
	v_mul_u32_u24_e32 v162, v158, v158
	v_mul_u32_u24_e32 v163, v159, v159
	v_mul_u32_u24_e32 v164, v160, v160
	v_cvt_f32_u32_e32 v161, v161
	v_cvt_f32_u32_e32 v162, v162
	v_cvt_f32_u32_e32 v163, v163
	v_cvt_f32_u32_e32 v164, v164
	v_lshrrev_b32_e32 v161, 23, v161
	v_lshrrev_b32_e32 v162, 23, v162
	v_lshrrev_b32_e32 v163, 23, v163
	v_lshrrev_b32_e32 v164, 23, v164
	v_add_u32_e32 v161, 0xffffff83, v161
	v_add_u32_e32 v162, 0xffffff83, v162
	v_add_u32_e32 v163, 0xffffff83, v163
	v_add_u32_e32 v164, 0xffffff83, v164
	v_min_u32_e32 v161, 15, v161
	v_min_u32_e32 v162, 15, v162
	v_min_u32_e32 v163, 15, v163
	v_min_u32_e32 v164, 15, v164
	v_cmp_gt_u32_e32 vcc, 8, v149
	v_cmp_gt_u32_e64 s[26:27], 8, v158
	v_cmp_gt_u32_e64 s[36:37], 8, v159
	v_cmp_gt_u32_e64 s[38:39], 8, v160
	v_med3_i32 v165, v145, 0, 1
	v_med3_i32 v166, v146, 0, 1
	v_med3_i32 v167, v147, 0, 1
	v_med3_i32 v168, v148, 0, 1
	v_cndmask_b32_e64 v161, v161, v149, vcc
	v_cndmask_b32_e64 v162, v162, v158, s[26:27]
	v_cndmask_b32_e64 v163, v163, v159, s[36:37]
	v_cndmask_b32_e64 v164, v164, v160, s[38:39]
	v_lshl_add_u32 v161, v165, 4, v161
	v_lshl_add_u32 v162, v166, 4, v162
	v_lshl_add_u32 v163, v167, 4, v163
	v_lshl_add_u32 v164, v168, 4, v164
	v_lshl_add_u32 v165, v161, 5, v25
	v_lshl_add_u32 v166, v162, 5, v25
	v_lshl_add_u32 v167, v163, 5, v25
	v_lshl_add_u32 v168, v164, 5, v25
	ds_read_b32 v165, v165
	ds_read_b32 v166, v166
	ds_read_b32 v167, v167
	ds_read_b32 v168, v168
	s_waitcnt lgkmcnt(3)
	v_fma_mixlo_f16 v165, v88, s3, v165
	s_waitcnt lgkmcnt(2)
	v_fma_mixlo_f16 v166, v89, s3, v166
	s_waitcnt lgkmcnt(1)
	v_fma_mixlo_f16 v167, v90, s3, v167
	s_waitcnt lgkmcnt(0)
	v_fma_mixlo_f16 v168, v91, s3, v168
	ds_write_b16 v143, v165 offset:2048
	ds_write_b16 v143, v166 offset:2064
	ds_write_b16 v143, v167 offset:2080
	ds_write_b16 v143, v168 offset:2096
	s_mov_b64 exec, s[12:13]
	s_cmp_le_i32 s16, 9
	s_cbranch_scc1 .Lqk_done
	ds_read_b64 v[92:93], v142 offset:288
	s_cmp_gt_i32 s16, 15
	s_cbranch_scc0 .Lqk_n6_9
	v_add_lshl_u32 v122, s48, v122, 8
	v_add_u32_e32 v122, v144, v122
	global_load_dwordx4 v[72:75], v122, s[84:85]
	global_load_dwordx4 v[76:79], v122, s[84:85] offset:64
	global_load_dwordx4 v[80:83], v122, s[84:85] offset:128
	global_load_dwordx4 v[84:87], v122, s[84:85] offset:192
	s_waitcnt vmcnt(24)
	s_branch .Lqk_go_9
.Lqk_n6_9:
	s_cmp_gt_i32 s16, 14
	s_cbranch_scc0 .Lqk_n5_9
	s_waitcnt vmcnt(20)
	s_branch .Lqk_go_9
.Lqk_n5_9:
	s_cmp_gt_i32 s16, 13
	s_cbranch_scc0 .Lqk_n4_9
	s_waitcnt vmcnt(16)
	s_branch .Lqk_go_9
.Lqk_n4_9:
	s_cmp_gt_i32 s16, 12
	s_cbranch_scc0 .Lqk_n3_9
	s_waitcnt vmcnt(12)
	s_branch .Lqk_go_9
.Lqk_n3_9:
	s_cmp_gt_i32 s16, 11
	s_cbranch_scc0 .Lqk_n2_9
	s_waitcnt vmcnt(8)
	s_branch .Lqk_go_9

; __device__ __forceinline__ void dsa_unit(int wv, const Args& A, LAS unsigned char* lds, int s, int qt) {
;     ...
;         for (int kt = 0; kt < nt; ++kt) {
;             long k1[8];
;             DSA_LOADT(k1, kt + 1);
;             f32x4 a = {0.f, 0.f, 0.f, 0.f};
; #pragma unroll
;             for (int kk = 0; kk < 8; ++kk) a = __builtin_amdgcn_mfma_f32_16x16x32_fp8_fp8(kf[kk], qf[kk], a, 0, 0, 0);
;             if (fr < 8) {
; #pragma unroll
;                 for (int r = 0; r < 4; ++r) { const int e2 = kt * 16 + fq * 4 + r; const int key2 = lst[e2];
;                     Pw[e2 * 8 + fr] = (h16)(a[r] * 0.0625f + relb[rel_bucket(key2 - qpos) * 8 + fr]); } }
.Lqk_go_9:
	v_mfma_f32_16x16x32_fp8_fp8 v[88:91], v[124:125], v[34:35], 0
	v_mfma_f32_16x16x32_fp8_fp8 v[88:91], v[126:127], v[32:33], v[88:91]
	v_mfma_f32_16x16x32_fp8_fp8 v[88:91], v[128:129], v[38:39], v[88:91]
	v_mfma_f32_16x16x32_fp8_fp8 v[88:91], v[130:131], v[36:37], v[88:91]
	v_mfma_f32_16x16x32_fp8_fp8 v[88:91], v[132:133], v[42:43], v[88:91]
	v_mfma_f32_16x16x32_fp8_fp8 v[88:91], v[134:135], v[40:41], v[88:91]
	v_mfma_f32_16x16x32_fp8_fp8 v[88:91], v[136:137], v[46:47], v[88:91]
	v_mfma_f32_16x16x32_fp8_fp8 v[88:91], v[138:139], v[44:45], v[88:91]
	s_and_saveexec_b64 s[12:13], s[8:9]
	s_waitcnt lgkmcnt(0)
	v_and_b32_e32 v145, 0xffff, v92
	v_lshrrev_b32_e32 v146, 16, v92
	v_and_b32_e32 v147, 0xffff, v93
	v_lshrrev_b32_e32 v148, 16, v93
	v_subrev_u32_e32 v145, s1, v145
	v_subrev_u32_e32 v146, s1, v146
	v_subrev_u32_e32 v147, s1, v147
	v_subrev_u32_e32 v148, s1, v148
	v_sub_u32_e32 v149, 0, v145
	v_sub_u32_e32 v158, 0, v146
	v_sub_u32_e32 v159, 0, v147
	v_sub_u32_e32 v160, 0, v148
	v_max_i32_e32 v149, v145, v149
	v_max_i32_e32 v158, v146, v158
	v_max_i32_e32 v159, v147, v159
	v_max_i32_e32 v160, v148, v160
	v_mul_u32_u24_e32 v161, v149, v149
	v_mul_u32_u24_e32 v162, v158, v158
	v_mul_u32_u24_e32 v163, v159, v159
	v_mul_u32_u24_e32 v164, v160, v160
	v_cvt_f32_u32_e32 v161, v161
	v_cvt_f32_u32_e32 v162, v162
	v_cvt_f32_u32_e32 v163, v163
	v_cvt_f32_u32_e32 v164, v164
	v_lshrrev_b32_e32 v161, 23, v161
	v_lshrrev_b32_e32 v162, 23, v162
	v_lshrrev_b32_e32 v163, 23, v163
	v_lshrrev_b32_e32 v164, 23, v164
	v_add_u32_e32 v161, 0xffffff83, v161
	v_add_u32_e32 v162, 0xffffff83, v162
	v_add_u32_e32 v163, 0xffffff83, v163
	v_add_u32_e32 v164, 0xffffff83, v164
	v_min_u32_e32 v161, 15, v161
	v_min_u32_e32 v162, 15, v162
	v_min_u32_e32 v163, 15, v163
	v_min_u32_e32 v164, 15, v164
	v_cmp_gt_u32_e32 vcc, 8, v149
	v_cmp_gt_u32_e64 s[26:27], 8, v158
	v_cmp_gt_u32_e64 s[36:37], 8, v159
	v_cmp_gt_u32_e64 s[38:39], 8, v160
	v_med3_i32 v165, v145, 0, 1
	v_med3_i32 v166, v146, 0, 1
	v_med3_i32 v167, v147, 0, 1
	v_med3_i32 v168, v148, 0, 1
	v_cndmask_b32_e64 v161, v161, v149, vcc
	v_cndmask_b32_e64 v162, v162, v158, s[26:27]
	v_cndmask_b32_e64 v163, v163, v159, s[36:37]
	v_cndmask_b32_e64 v164, v164, v160, s[38:39]
	v_lshl_add_u32 v161, v165, 4, v161
	v_lshl_add_u32 v162, v166, 4, v162
	v_lshl_add_u32 v163, v167, 4, v163
	v_lshl_add_u32 v164, v168, 4, v164
	v_lshl_add_u32 v165, v161, 5, v25
	v_lshl_add_u32 v166, v162, 5, v25
	v_lshl_add_u32 v167, v163, 5, v25
	v_lshl_add_u32 v168, v164, 5, v25
	ds_read_b32 v165, v165
	ds_read_b32 v166, v166
	ds_read_b32 v167, v167
	ds_read_b32 v168, v168
	s_waitcnt lgkmcnt(3)
	v_fma_mixlo_f16 v165, v88, s3, v165
	s_waitcnt lgkmcnt(2)
	v_fma_mixlo_f16 v166, v89, s3, v166
	s_waitcnt lgkmcnt(1)
	v_fma_mixlo_f16 v167, v90, s3, v167
	s_waitcnt lgkmcnt(0)
	v_fma_mixlo_f16 v168, v91, s3, v168
	ds_write_b16 v143, v165 offset:2304
	ds_write_b16 v143, v166 offset:2320
	ds_write_b16 v143, v167 offset:2336
	ds_write_b16 v143, v168 offset:2352
	s_mov_b64 exec, s[12:13]
	s_cmp_le_i32 s16, 10
	s_cbranch_scc1 .Lqk_done
	ds_read_b64 v[92:93], v142 offset:320
	s_cmp_gt_i32 s16, 15
	s_cbranch_scc0 .Lqk_n5_10
	s_waitcnt vmcnt(20)
	s_branch .Lqk_go_10
.Lqk_n5_10:
	s_cmp_gt_i32 s16, 14
	s_cbranch_scc0 .Lqk_n4_10
	s_waitcnt vmcnt(16)
	s_branch .Lqk_go_10
.Lqk_n4_10:
	s_cmp_gt_i32 s16, 13
	s_cbranch_scc0 .Lqk_n3_10
	s_waitcnt vmcnt(12)
	s_branch .Lqk_go_10
.Lqk_n3_10:
	s_cmp_gt_i32 s16, 12
	s_cbranch_scc0 .Lqk_n2_10
	s_waitcnt vmcnt(8)
	s_branch .Lqk_go_10

; __device__ __forceinline__ void dsa_unit(int wv, const Args& A, LAS unsigned char* lds, int s, int qt) {
;     ...
;         for (int kt = 0; kt < nt; ++kt) {
;             long k1[8];
;             DSA_LOADT(k1, kt + 1);
;             f32x4 a = {0.f, 0.f, 0.f, 0.f};
; #pragma unroll
;             for (int kk = 0; kk < 8; ++kk) a = __builtin_amdgcn_mfma_f32_16x16x32_fp8_fp8(kf[kk], qf[kk], a, 0, 0, 0);
;             if (fr < 8) {
; #pragma unroll
;                 for (int r = 0; r < 4; ++r) { const int e2 = kt * 16 + fq * 4 + r; const int key2 = lst[e2];
;                     Pw[e2 * 8 + fr] = (h16)(a[r] * 0.0625f + relb[rel_bucket(key2 - qpos) * 8 + fr]); } }
.Lqk_go_10:
	v_mfma_f32_16x16x32_fp8_fp8 v[88:91], v[180:181], v[34:35], 0
	v_mfma_f32_16x16x32_fp8_fp8 v[88:91], v[182:183], v[32:33], v[88:91]
	v_mfma_f32_16x16x32_fp8_fp8 v[88:91], v[184:185], v[38:39], v[88:91]
	v_mfma_f32_16x16x32_fp8_fp8 v[88:91], v[186:187], v[36:37], v[88:91]
	v_mfma_f32_16x16x32_fp8_fp8 v[88:91], v[188:189], v[42:43], v[88:91]
	v_mfma_f32_16x16x32_fp8_fp8 v[88:91], v[190:191], v[40:41], v[88:91]
	v_mfma_f32_16x16x32_fp8_fp8 v[88:91], v[192:193], v[46:47], v[88:91]
	v_mfma_f32_16x16x32_fp8_fp8 v[88:91], v[194:195], v[44:45], v[88:91]
	s_and_saveexec_b64 s[12:13], s[8:9]
	s_waitcnt lgkmcnt(0)
	v_and_b32_e32 v145, 0xffff, v92
	v_lshrrev_b32_e32 v146, 16, v92
	v_and_b32_e32 v147, 0xffff, v93
	v_lshrrev_b32_e32 v148, 16, v93
	v_subrev_u32_e32 v145, s1, v145
	v_subrev_u32_e32 v146, s1, v146
	v_subrev_u32_e32 v147, s1, v147
	v_subrev_u32_e32 v148, s1, v148
	v_sub_u32_e32 v149, 0, v145
	v_sub_u32_e32 v158, 0, v146
	v_sub_u32_e32 v159, 0, v147
	v_sub_u32_e32 v160, 0, v148
	v_max_i32_e32 v149, v145, v149
	v_max_i32_e32 v158, v146, v158
	v_max_i32_e32 v159, v147, v159
	v_max_i32_e32 v160, v148, v160
	v_mul_u32_u24_e32 v161, v149, v149
	v_mul_u32_u24_e32 v162, v158, v158
	v_mul_u32_u24_e32 v163, v159, v159
	v_mul_u32_u24_e32 v164, v160, v160
	v_cvt_f32_u32_e32 v161, v161
	v_cvt_f32_u32_e32 v162, v162
	v_cvt_f32_u32_e32 v163, v163
	v_cvt_f32_u32_e32 v164, v164
	v_lshrrev_b32_e32 v161, 23, v161
	v_lshrrev_b32_e32 v162, 23, v162
	v_lshrrev_b32_e32 v163, 23, v163
	v_lshrrev_b32_e32 v164, 23, v164
	v_add_u32_e32 v161, 0xffffff83, v161
	v_add_u32_e32 v162, 0xffffff83, v162
	v_add_u32_e32 v163, 0xffffff83, v163
	v_add_u32_e32 v164, 0xffffff83, v164
	v_min_u32_e32 v161, 15, v161
	v_min_u32_e32 v162, 15, v162
	v_min_u32_e32 v163, 15, v163
	v_min_u32_e32 v164, 15, v164
	v_cmp_gt_u32_e32 vcc, 8, v149
	v_cmp_gt_u32_e64 s[26:27], 8, v158
	v_cmp_gt_u32_e64 s[36:37], 8, v159
	v_cmp_gt_u32_e64 s[38:39], 8, v160
	v_med3_i32 v165, v145, 0, 1
	v_med3_i32 v166, v146, 0, 1
	v_med3_i32 v167, v147, 0, 1
	v_med3_i32 v168, v148, 0, 1
	v_cndmask_b32_e64 v161, v161, v149, vcc
	v_cndmask_b32_e64 v162, v162, v158, s[26:27]
	v_cndmask_b32_e64 v163, v163, v159, s[36:37]
	v_cndmask_b32_e64 v164, v164, v160, s[38:39]
	v_lshl_add_u32 v161, v165, 4, v161
	v_lshl_add_u32 v162, v166, 4, v162
	v_lshl_add_u32 v163, v167, 4, v163
	v_lshl_add_u32 v164, v168, 4, v164
	v_lshl_add_u32 v165, v161, 5, v25
	v_lshl_add_u32 v166, v162, 5, v25
	v_lshl_add_u32 v167, v163, 5, v25
	v_lshl_add_u32 v168, v164, 5, v25
	ds_read_b32 v165, v165
	ds_read_b32 v166, v166
	ds_read_b32 v167, v167
	ds_read_b32 v168, v168
	s_waitcnt lgkmcnt(3)
	v_fma_mixlo_f16 v165, v88, s3, v165
	s_waitcnt lgkmcnt(2)
	v_fma_mixlo_f16 v166, v89, s3, v166
	s_waitcnt lgkmcnt(1)
	v_fma_mixlo_f16 v167, v90, s3, v167
	s_waitcnt lgkmcnt(0)
	v_fma_mixlo_f16 v168, v91, s3, v168
	ds_write_b16 v143, v165 offset:2560
	ds_write_b16 v143, v166 offset:2576
	ds_write_b16 v143, v167 offset:2592
	ds_write_b16 v143, v168 offset:2608
	s_mov_b64 exec, s[12:13]
	s_cmp_le_i32 s16, 11
	s_cbranch_scc1 .Lqk_done
	ds_read_b64 v[92:93], v142 offset:352
	s_cmp_gt_i32 s16, 15
	s_cbranch_scc0 .Lqk_n4_11
	s_waitcnt vmcnt(16)
	s_branch .Lqk_go_11
.Lqk_n4_11:
	s_cmp_gt_i32 s16, 14
	s_cbranch_scc0 .Lqk_n3_11
	s_waitcnt vmcnt(12)
	s_branch .Lqk_go_11
.Lqk_n3_11:
	s_cmp_gt_i32 s16, 13
	s_cbranch_scc0 .Lqk_n2_11
	s_waitcnt vmcnt(8)
	s_branch .Lqk_go_11

; __device__ __forceinline__ void dsa_unit(int wv, const Args& A, LAS unsigned char* lds, int s, int qt) {
;     ...
;         for (int kt = 0; kt < nt; ++kt) {
;             long k1[8];
;             DSA_LOADT(k1, kt + 1);
;             f32x4 a = {0.f, 0.f, 0.f, 0.f};
; #pragma unroll
;             for (int kk = 0; kk < 8; ++kk) a = __builtin_amdgcn_mfma_f32_16x16x32_fp8_fp8(kf[kk], qf[kk], a, 0, 0, 0);
;             if (fr < 8) {
; #pragma unroll
;                 for (int r = 0; r < 4; ++r) { const int e2 = kt * 16 + fq * 4 + r; const int key2 = lst[e2];
;                     Pw[e2 * 8 + fr] = (h16)(a[r] * 0.0625f + relb[rel_bucket(key2 - qpos) * 8 + fr]); } }
.Lqk_go_11:
	v_mfma_f32_16x16x32_fp8_fp8 v[88:91], v[196:197], v[34:35], 0
	v_mfma_f32_16x16x32_fp8_fp8 v[88:91], v[198:199], v[32:33], v[88:91]
	v_mfma_f32_16x16x32_fp8_fp8 v[88:91], v[200:201], v[38:39], v[88:91]
	v_mfma_f32_16x16x32_fp8_fp8 v[88:91], v[202:203], v[36:37], v[88:91]
	v_mfma_f32_16x16x32_fp8_fp8 v[88:91], v[204:205], v[42:43], v[88:91]
	v_mfma_f32_16x16x32_fp8_fp8 v[88:91], v[206:207], v[40:41], v[88:91]
	v_mfma_f32_16x16x32_fp8_fp8 v[88:91], v[208:209], v[46:47], v[88:91]
	v_mfma_f32_16x16x32_fp8_fp8 v[88:91], v[210:211], v[44:45], v[88:91]
	s_and_saveexec_b64 s[12:13], s[8:9]
	s_waitcnt lgkmcnt(0)
	v_and_b32_e32 v145, 0xffff, v92
	v_lshrrev_b32_e32 v146, 16, v92
	v_and_b32_e32 v147, 0xffff, v93
	v_lshrrev_b32_e32 v148, 16, v93
	v_subrev_u32_e32 v145, s1, v145
	v_subrev_u32_e32 v146, s1, v146
	v_subrev_u32_e32 v147, s1, v147
	v_subrev_u32_e32 v148, s1, v148
	v_sub_u32_e32 v149, 0, v145
	v_sub_u32_e32 v158, 0, v146
	v_sub_u32_e32 v159, 0, v147
	v_sub_u32_e32 v160, 0, v148
	v_max_i32_e32 v149, v145, v149
	v_max_i32_e32 v158, v146, v158
	v_max_i32_e32 v159, v147, v159
	v_max_i32_e32 v160, v148, v160
	v_mul_u32_u24_e32 v161, v149, v149
	v_mul_u32_u24_e32 v162, v158, v158
	v_mul_u32_u24_e32 v163, v159, v159
	v_mul_u32_u24_e32 v164, v160, v160
	v_cvt_f32_u32_e32 v161, v161
	v_cvt_f32_u32_e32 v162, v162
	v_cvt_f32_u32_e32 v163, v163
	v_cvt_f32_u32_e32 v164, v164
	v_lshrrev_b32_e32 v161, 23, v161
	v_lshrrev_b32_e32 v162, 23, v162
	v_lshrrev_b32_e32 v163, 23, v163
	v_lshrrev_b32_e32 v164, 23, v164
	v_add_u32_e32 v161, 0xffffff83, v161
	v_add_u32_e32 v162, 0xffffff83, v162
	v_add_u32_e32 v163, 0xffffff83, v163
	v_add_u32_e32 v164, 0xffffff83, v164
	v_min_u32_e32 v161, 15, v161
	v_min_u32_e32 v162, 15, v162
	v_min_u32_e32 v163, 15, v163
	v_min_u32_e32 v164, 15, v164
	v_cmp_gt_u32_e32 vcc, 8, v149
	v_cmp_gt_u32_e64 s[26:27], 8, v158
	v_cmp_gt_u32_e64 s[36:37], 8, v159
	v_cmp_gt_u32_e64 s[38:39], 8, v160
	v_med3_i32 v165, v145, 0, 1
	v_med3_i32 v166, v146, 0, 1
	v_med3_i32 v167, v147, 0, 1
	v_med3_i32 v168, v148, 0, 1
	v_cndmask_b32_e64 v161, v161, v149, vcc
	v_cndmask_b32_e64 v162, v162, v158, s[26:27]
	v_cndmask_b32_e64 v163, v163, v159, s[36:37]
	v_cndmask_b32_e64 v164, v164, v160, s[38:39]
	v_lshl_add_u32 v161, v165, 4, v161
	v_lshl_add_u32 v162, v166, 4, v162
	v_lshl_add_u32 v163, v167, 4, v163
	v_lshl_add_u32 v164, v168, 4, v164
	v_lshl_add_u32 v165, v161, 5, v25
	v_lshl_add_u32 v166, v162, 5, v25
	v_lshl_add_u32 v167, v163, 5, v25
	v_lshl_add_u32 v168, v164, 5, v25
	ds_read_b32 v165, v165
	ds_read_b32 v166, v166
	ds_read_b32 v167, v167
	ds_read_b32 v168, v168
	s_waitcnt lgkmcnt(3)
	v_fma_mixlo_f16 v165, v88, s3, v165
	s_waitcnt lgkmcnt(2)
	v_fma_mixlo_f16 v166, v89, s3, v166
	s_waitcnt lgkmcnt(1)
	v_fma_mixlo_f16 v167, v90, s3, v167
	s_waitcnt lgkmcnt(0)
	v_fma_mixlo_f16 v168, v91, s3, v168
	ds_write_b16 v143, v165 offset:2816
	ds_write_b16 v143, v166 offset:2832
	ds_write_b16 v143, v167 offset:2848
	ds_write_b16 v143, v168 offset:2864
	s_mov_b64 exec, s[12:13]
	s_cmp_le_i32 s16, 12
	s_cbranch_scc1 .Lqk_done
	ds_read_b64 v[92:93], v142 offset:384
	s_cmp_gt_i32 s16, 15
	s_cbranch_scc0 .Lqk_n3_12
	s_waitcnt vmcnt(12)
	s_branch .Lqk_go_12
.Lqk_n3_12:
	s_cmp_gt_i32 s16, 14
	s_cbranch_scc0 .Lqk_n2_12
	s_waitcnt vmcnt(8)
	s_branch .Lqk_go_12

; __device__ __forceinline__ void dsa_unit(int wv, const Args& A, LAS unsigned char* lds, int s, int qt) {
;     ...
;         for (int kt = 0; kt < nt; ++kt) {
;             long k1[8];
;             DSA_LOADT(k1, kt + 1);
;             f32x4 a = {0.f, 0.f, 0.f, 0.f};
; #pragma unroll
;             for (int kk = 0; kk < 8; ++kk) a = __builtin_amdgcn_mfma_f32_16x16x32_fp8_fp8(kf[kk], qf[kk], a, 0, 0, 0);
;             if (fr < 8) {
; #pragma unroll
;                 for (int r = 0; r < 4; ++r) { const int e2 = kt * 16 + fq * 4 + r; const int key2 = lst[e2];
;                     Pw[e2 * 8 + fr] = (h16)(a[r] * 0.0625f + relb[rel_bucket(key2 - qpos) * 8 + fr]); } }
.Lqk_go_12:
	v_mfma_f32_16x16x32_fp8_fp8 v[88:91], v[212:213], v[34:35], 0
	v_mfma_f32_16x16x32_fp8_fp8 v[88:91], v[214:215], v[32:33], v[88:91]
	v_mfma_f32_16x16x32_fp8_fp8 v[88:91], v[216:217], v[38:39], v[88:91]
	v_mfma_f32_16x16x32_fp8_fp8 v[88:91], v[218:219], v[36:37], v[88:91]
	v_mfma_f32_16x16x32_fp8_fp8 v[88:91], v[220:221], v[42:43], v[88:91]
	v_mfma_f32_16x16x32_fp8_fp8 v[88:91], v[222:223], v[40:41], v[88:91]
	v_mfma_f32_16x16x32_fp8_fp8 v[88:91], v[224:225], v[46:47], v[88:91]
	v_mfma_f32_16x16x32_fp8_fp8 v[88:91], v[226:227], v[44:45], v[88:91]
	s_and_saveexec_b64 s[12:13], s[8:9]
	s_waitcnt lgkmcnt(0)
	v_and_b32_e32 v145, 0xffff, v92
	v_lshrrev_b32_e32 v146, 16, v92
	v_and_b32_e32 v147, 0xffff, v93
	v_lshrrev_b32_e32 v148, 16, v93
	v_subrev_u32_e32 v145, s1, v145
	v_subrev_u32_e32 v146, s1, v146
	v_subrev_u32_e32 v147, s1, v147
	v_subrev_u32_e32 v148, s1, v148
	v_sub_u32_e32 v149, 0, v145
	v_sub_u32_e32 v158, 0, v146
	v_sub_u32_e32 v159, 0, v147
	v_sub_u32_e32 v160, 0, v148
	v_max_i32_e32 v149, v145, v149
	v_max_i32_e32 v158, v146, v158
	v_max_i32_e32 v159, v147, v159
	v_max_i32_e32 v160, v148, v160
	v_mul_u32_u24_e32 v161, v149, v149
	v_mul_u32_u24_e32 v162, v158, v158
	v_mul_u32_u24_e32 v163, v159, v159
	v_mul_u32_u24_e32 v164, v160, v160
	v_cvt_f32_u32_e32 v161, v161
	v_cvt_f32_u32_e32 v162, v162
	v_cvt_f32_u32_e32 v163, v163
	v_cvt_f32_u32_e32 v164, v164
	v_lshrrev_b32_e32 v161, 23, v161
	v_lshrrev_b32_e32 v162, 23, v162
	v_lshrrev_b32_e32 v163, 23, v163
	v_lshrrev_b32_e32 v164, 23, v164
	v_add_u32_e32 v161, 0xffffff83, v161
	v_add_u32_e32 v162, 0xffffff83, v162
	v_add_u32_e32 v163, 0xffffff83, v163
	v_add_u32_e32 v164, 0xffffff83, v164
	v_min_u32_e32 v161, 15, v161
	v_min_u32_e32 v162, 15, v162
	v_min_u32_e32 v163, 15, v163
	v_min_u32_e32 v164, 15, v164
	v_cmp_gt_u32_e32 vcc, 8, v149
	v_cmp_gt_u32_e64 s[26:27], 8, v158
	v_cmp_gt_u32_e64 s[36:37], 8, v159
	v_cmp_gt_u32_e64 s[38:39], 8, v160
	v_med3_i32 v165, v145, 0, 1
	v_med3_i32 v166, v146, 0, 1
	v_med3_i32 v167, v147, 0, 1
	v_med3_i32 v168, v148, 0, 1
	v_cndmask_b32_e64 v161, v161, v149, vcc
	v_cndmask_b32_e64 v162, v162, v158, s[26:27]
	v_cndmask_b32_e64 v163, v163, v159, s[36:37]
	v_cndmask_b32_e64 v164, v164, v160, s[38:39]
	v_lshl_add_u32 v161, v165, 4, v161
	v_lshl_add_u32 v162, v166, 4, v162
	v_lshl_add_u32 v163, v167, 4, v163
	v_lshl_add_u32 v164, v168, 4, v164
	v_lshl_add_u32 v165, v161, 5, v25
	v_lshl_add_u32 v166, v162, 5, v25
	v_lshl_add_u32 v167, v163, 5, v25
	v_lshl_add_u32 v168, v164, 5, v25
	ds_read_b32 v165, v165
	ds_read_b32 v166, v166
	ds_read_b32 v167, v167
	ds_read_b32 v168, v168
	s_waitcnt lgkmcnt(3)
	v_fma_mixlo_f16 v165, v88, s3, v165
	s_waitcnt lgkmcnt(2)
	v_fma_mixlo_f16 v166, v89, s3, v166
	s_waitcnt lgkmcnt(1)
	v_fma_mixlo_f16 v167, v90, s3, v167
	s_waitcnt lgkmcnt(0)
	v_fma_mixlo_f16 v168, v91, s3, v168
	ds_write_b16 v143, v165 offset:3072
	ds_write_b16 v143, v166 offset:3088
	ds_write_b16 v143, v167 offset:3104
	ds_write_b16 v143, v168 offset:3120
	s_mov_b64 exec, s[12:13]
	s_cmp_le_i32 s16, 13
	s_cbranch_scc1 .Lqk_done
	ds_read_b64 v[92:93], v142 offset:416
	s_cmp_gt_i32 s16, 15
	s_cbranch_scc0 .Lqk_n2_13
	s_waitcnt vmcnt(8)
	s_branch .Lqk_go_13

; __device__ __forceinline__ void dsa_unit(int wv, const Args& A, LAS unsigned char* lds, int s, int qt) {
;     ...
;         for (int kt = 0; kt < nt; ++kt) {
;             long k1[8];
;             DSA_LOADT(k1, kt + 1);
;             f32x4 a = {0.f, 0.f, 0.f, 0.f};
; #pragma unroll
;             for (int kk = 0; kk < 8; ++kk) a = __builtin_amdgcn_mfma_f32_16x16x32_fp8_fp8(kf[kk], qf[kk], a, 0, 0, 0);
;             if (fr < 8) {
; #pragma unroll
;                 for (int r = 0; r < 4; ++r) { const int e2 = kt * 16 + fq * 4 + r; const int key2 = lst[e2];
;                     Pw[e2 * 8 + fr] = (h16)(a[r] * 0.0625f + relb[rel_bucket(key2 - qpos) * 8 + fr]); } }
.Lqk_go_13:
	v_mfma_f32_16x16x32_fp8_fp8 v[88:91], v[240:241], v[34:35], 0
	v_mfma_f32_16x16x32_fp8_fp8 v[88:91], v[242:243], v[32:33], v[88:91]
	v_mfma_f32_16x16x32_fp8_fp8 v[88:91], v[244:245], v[38:39], v[88:91]
	v_mfma_f32_16x16x32_fp8_fp8 v[88:91], v[246:247], v[36:37], v[88:91]
	v_mfma_f32_16x16x32_fp8_fp8 v[88:91], v[248:249], v[42:43], v[88:91]
	v_mfma_f32_16x16x32_fp8_fp8 v[88:91], v[250:251], v[40:41], v[88:91]
	v_mfma_f32_16x16x32_fp8_fp8 v[88:91], v[252:253], v[46:47], v[88:91]
	v_mfma_f32_16x16x32_fp8_fp8 v[88:91], v[254:255], v[44:45], v[88:91]
	s_and_saveexec_b64 s[12:13], s[8:9]
	s_waitcnt lgkmcnt(0)
	v_and_b32_e32 v145, 0xffff, v92
	v_lshrrev_b32_e32 v146, 16, v92
	v_and_b32_e32 v147, 0xffff, v93
	v_lshrrev_b32_e32 v148, 16, v93
	v_subrev_u32_e32 v145, s1, v145
	v_subrev_u32_e32 v146, s1, v146
	v_subrev_u32_e32 v147, s1, v147
	v_subrev_u32_e32 v148, s1, v148
	v_sub_u32_e32 v149, 0, v145
	v_sub_u32_e32 v158, 0, v146
	v_sub_u32_e32 v159, 0, v147
	v_sub_u32_e32 v160, 0, v148
	v_max_i32_e32 v149, v145, v149
	v_max_i32_e32 v158, v146, v158
	v_max_i32_e32 v159, v147, v159
	v_max_i32_e32 v160, v148, v160
	v_mul_u32_u24_e32 v161, v149, v149
	v_mul_u32_u24_e32 v162, v158, v158
	v_mul_u32_u24_e32 v163, v159, v159
	v_mul_u32_u24_e32 v164, v160, v160
	v_cvt_f32_u32_e32 v161, v161
	v_cvt_f32_u32_e32 v162, v162
	v_cvt_f32_u32_e32 v163, v163
	v_cvt_f32_u32_e32 v164, v164
	v_lshrrev_b32_e32 v161, 23, v161
	v_lshrrev_b32_e32 v162, 23, v162
	v_lshrrev_b32_e32 v163, 23, v163
	v_lshrrev_b32_e32 v164, 23, v164
	v_add_u32_e32 v161, 0xffffff83, v161
	v_add_u32_e32 v162, 0xffffff83, v162
	v_add_u32_e32 v163, 0xffffff83, v163
	v_add_u32_e32 v164, 0xffffff83, v164
	v_min_u32_e32 v161, 15, v161
	v_min_u32_e32 v162, 15, v162
	v_min_u32_e32 v163, 15, v163
	v_min_u32_e32 v164, 15, v164
	v_cmp_gt_u32_e32 vcc, 8, v149
	v_cmp_gt_u32_e64 s[26:27], 8, v158
	v_cmp_gt_u32_e64 s[36:37], 8, v159
	v_cmp_gt_u32_e64 s[38:39], 8, v160
	v_med3_i32 v165, v145, 0, 1
	v_med3_i32 v166, v146, 0, 1
	v_med3_i32 v167, v147, 0, 1
	v_med3_i32 v168, v148, 0, 1
	v_cndmask_b32_e64 v161, v161, v149, vcc
	v_cndmask_b32_e64 v162, v162, v158, s[26:27]
	v_cndmask_b32_e64 v163, v163, v159, s[36:37]
	v_cndmask_b32_e64 v164, v164, v160, s[38:39]
	v_lshl_add_u32 v161, v165, 4, v161
	v_lshl_add_u32 v162, v166, 4, v162
	v_lshl_add_u32 v163, v167, 4, v163
	v_lshl_add_u32 v164, v168, 4, v164
	v_lshl_add_u32 v165, v161, 5, v25
	v_lshl_add_u32 v166, v162, 5, v25
	v_lshl_add_u32 v167, v163, 5, v25
	v_lshl_add_u32 v168, v164, 5, v25
	ds_read_b32 v165, v165
	ds_read_b32 v166, v166
	ds_read_b32 v167, v167
	ds_read_b32 v168, v168
	s_waitcnt lgkmcnt(3)
	v_fma_mixlo_f16 v165, v88, s3, v165
	s_waitcnt lgkmcnt(2)
	v_fma_mixlo_f16 v166, v89, s3, v166
	s_waitcnt lgkmcnt(1)
	v_fma_mixlo_f16 v167, v90, s3, v167
	s_waitcnt lgkmcnt(0)
	v_fma_mixlo_f16 v168, v91, s3, v168
	ds_write_b16 v143, v165 offset:3328
	ds_write_b16 v143, v166 offset:3344
	ds_write_b16 v143, v167 offset:3360
	ds_write_b16 v143, v168 offset:3376
	s_mov_b64 exec, s[12:13]
	s_cmp_le_i32 s16, 14
	s_cbranch_scc1 .Lqk_done
	ds_read_b64 v[92:93], v142 offset:448
	s_cmp_gt_i32 s16, 15
	s_cbranch_scc0 .Lqk_n1_14
	s_waitcnt vmcnt(4)
	s_branch .Lqk_go_14

; __device__ __forceinline__ void dsa_unit(int wv, const Args& A, LAS unsigned char* lds, int s, int qt) {
;     ...
;         for (int kt = 0; kt < nt; ++kt) {
;             long k1[8];
;             DSA_LOADT(k1, kt + 1);
;             f32x4 a = {0.f, 0.f, 0.f, 0.f};
; #pragma unroll
;             for (int kk = 0; kk < 8; ++kk) a = __builtin_amdgcn_mfma_f32_16x16x32_fp8_fp8(kf[kk], qf[kk], a, 0, 0, 0);
;             if (fr < 8) {
; #pragma unroll
;                 for (int r = 0; r < 4; ++r) { const int e2 = kt * 16 + fq * 4 + r; const int key2 = lst[e2];
;                     Pw[e2 * 8 + fr] = (h16)(a[r] * 0.0625f + relb[rel_bucket(key2 - qpos) * 8 + fr]); } }
.Lqk_go_14:
	v_mfma_f32_16x16x32_fp8_fp8 v[88:91], v[56:57], v[34:35], 0
	v_mfma_f32_16x16x32_fp8_fp8 v[88:91], v[58:59], v[32:33], v[88:91]
	v_mfma_f32_16x16x32_fp8_fp8 v[88:91], v[60:61], v[38:39], v[88:91]
	v_mfma_f32_16x16x32_fp8_fp8 v[88:91], v[62:63], v[36:37], v[88:91]
	v_mfma_f32_16x16x32_fp8_fp8 v[88:91], v[64:65], v[42:43], v[88:91]
	v_mfma_f32_16x16x32_fp8_fp8 v[88:91], v[66:67], v[40:41], v[88:91]
	v_mfma_f32_16x16x32_fp8_fp8 v[88:91], v[68:69], v[46:47], v[88:91]
	v_mfma_f32_16x16x32_fp8_fp8 v[88:91], v[70:71], v[44:45], v[88:91]
	s_and_saveexec_b64 s[12:13], s[8:9]
	s_waitcnt lgkmcnt(0)
	v_and_b32_e32 v145, 0xffff, v92
	v_lshrrev_b32_e32 v146, 16, v92
	v_and_b32_e32 v147, 0xffff, v93
	v_lshrrev_b32_e32 v148, 16, v93
	v_subrev_u32_e32 v145, s1, v145
	v_subrev_u32_e32 v146, s1, v146
	v_subrev_u32_e32 v147, s1, v147
	v_subrev_u32_e32 v148, s1, v148
	v_sub_u32_e32 v149, 0, v145
	v_sub_u32_e32 v158, 0, v146
	v_sub_u32_e32 v159, 0, v147
	v_sub_u32_e32 v160, 0, v148
	v_max_i32_e32 v149, v145, v149
	v_max_i32_e32 v158, v146, v158
	v_max_i32_e32 v159, v147, v159
	v_max_i32_e32 v160, v148, v160
	v_mul_u32_u24_e32 v161, v149, v149
	v_mul_u32_u24_e32 v162, v158, v158
	v_mul_u32_u24_e32 v163, v159, v159
	v_mul_u32_u24_e32 v164, v160, v160
	v_cvt_f32_u32_e32 v161, v161
	v_cvt_f32_u32_e32 v162, v162
	v_cvt_f32_u32_e32 v163, v163
	v_cvt_f32_u32_e32 v164, v164
	v_lshrrev_b32_e32 v161, 23, v161
	v_lshrrev_b32_e32 v162, 23, v162
	v_lshrrev_b32_e32 v163, 23, v163
	v_lshrrev_b32_e32 v164, 23, v164
	v_add_u32_e32 v161, 0xffffff83, v161
	v_add_u32_e32 v162, 0xffffff83, v162
	v_add_u32_e32 v163, 0xffffff83, v163
	v_add_u32_e32 v164, 0xffffff83, v164
	v_min_u32_e32 v161, 15, v161
	v_min_u32_e32 v162, 15, v162
	v_min_u32_e32 v163, 15, v163
	v_min_u32_e32 v164, 15, v164
	v_cmp_gt_u32_e32 vcc, 8, v149
	v_cmp_gt_u32_e64 s[26:27], 8, v158
	v_cmp_gt_u32_e64 s[36:37], 8, v159
	v_cmp_gt_u32_e64 s[38:39], 8, v160
	v_med3_i32 v165, v145, 0, 1
	v_med3_i32 v166, v146, 0, 1
	v_med3_i32 v167, v147, 0, 1
	v_med3_i32 v168, v148, 0, 1
	v_cndmask_b32_e64 v161, v161, v149, vcc
	v_cndmask_b32_e64 v162, v162, v158, s[26:27]
	v_cndmask_b32_e64 v163, v163, v159, s[36:37]
	v_cndmask_b32_e64 v164, v164, v160, s[38:39]
	v_lshl_add_u32 v161, v165, 4, v161
	v_lshl_add_u32 v162, v166, 4, v162
	v_lshl_add_u32 v163, v167, 4, v163
	v_lshl_add_u32 v164, v168, 4, v164
	v_lshl_add_u32 v165, v161, 5, v25
	v_lshl_add_u32 v166, v162, 5, v25
	v_lshl_add_u32 v167, v163, 5, v25
	v_lshl_add_u32 v168, v164, 5, v25
	ds_read_b32 v165, v165
	ds_read_b32 v166, v166
	ds_read_b32 v167, v167
	ds_read_b32 v168, v168
	s_waitcnt lgkmcnt(3)
	v_fma_mixlo_f16 v165, v88, s3, v165
	s_waitcnt lgkmcnt(2)
	v_fma_mixlo_f16 v166, v89, s3, v166
	s_waitcnt lgkmcnt(1)
	v_fma_mixlo_f16 v167, v90, s3, v167
	s_waitcnt lgkmcnt(0)
	v_fma_mixlo_f16 v168, v91, s3, v168
	ds_write_b16 v143, v165 offset:3584
	ds_write_b16 v143, v166 offset:3600
	ds_write_b16 v143, v167 offset:3616
	ds_write_b16 v143, v168 offset:3632
	s_mov_b64 exec, s[12:13]
	s_cmp_le_i32 s16, 15
	s_cbranch_scc1 .Lqk_done
	ds_read_b64 v[92:93], v142 offset:480
	s_waitcnt vmcnt(0)
.Lqk_go_15:
	v_mfma_f32_16x16x32_fp8_fp8 v[88:91], v[72:73], v[34:35], 0
	v_mfma_f32_16x16x32_fp8_fp8 v[88:91], v[74:75], v[32:33], v[88:91]
	v_mfma_f32_16x16x32_fp8_fp8 v[88:91], v[76:77], v[38:39], v[88:91]
	v_mfma_f32_16x16x32_fp8_fp8 v[88:91], v[78:79], v[36:37], v[88:91]
	v_mfma_f32_16x16x32_fp8_fp8 v[88:91], v[80:81], v[42:43], v[88:91]
	v_mfma_f32_16x16x32_fp8_fp8 v[88:91], v[82:83], v[40:41], v[88:91]
	v_mfma_f32_16x16x32_fp8_fp8 v[88:91], v[84:85], v[46:47], v[88:91]
	v_mfma_f32_16x16x32_fp8_fp8 v[88:91], v[86:87], v[44:45], v[88:91]
	s_and_saveexec_b64 s[12:13], s[8:9]
	s_waitcnt lgkmcnt(0)
	v_and_b32_e32 v145, 0xffff, v92
	v_lshrrev_b32_e32 v146, 16, v92
	v_and_b32_e32 v147, 0xffff, v93
	v_lshrrev_b32_e32 v148, 16, v93
	v_subrev_u32_e32 v145, s1, v145
	v_subrev_u32_e32 v146, s1, v146
	v_subrev_u32_e32 v147, s1, v147
	v_subrev_u32_e32 v148, s1, v148
	v_sub_u32_e32 v149, 0, v145
	v_sub_u32_e32 v158, 0, v146
	v_sub_u32_e32 v159, 0, v147
	v_sub_u32_e32 v160, 0, v148
	v_max_i32_e32 v149, v145, v149
	v_max_i32_e32 v158, v146, v158
	v_max_i32_e32 v159, v147, v159
	v_max_i32_e32 v160, v148, v160
	v_mul_u32_u24_e32 v161, v149, v149
	v_mul_u32_u24_e32 v162, v158, v158
	v_mul_u32_u24_e32 v163, v159, v159
	v_mul_u32_u24_e32 v164, v160, v160
	v_cvt_f32_u32_e32 v161, v161
	v_cvt_f32_u32_e32 v162, v162
	v_cvt_f32_u32_e32 v163, v163
	v_cvt_f32_u32_e32 v164, v164
	v_lshrrev_b32_e32 v161, 23, v161
	v_lshrrev_b32_e32 v162, 23, v162
	v_lshrrev_b32_e32 v163, 23, v163
	v_lshrrev_b32_e32 v164, 23, v164
	v_add_u32_e32 v161, 0xffffff83, v161
	v_add_u32_e32 v162, 0xffffff83, v162
	v_add_u32_e32 v163, 0xffffff83, v163
	v_add_u32_e32 v164, 0xffffff83, v164
	v_min_u32_e32 v161, 15, v161
	v_min_u32_e32 v162, 15, v162
	v_min_u32_e32 v163, 15, v163
	v_min_u32_e32 v164, 15, v164
	v_cmp_gt_u32_e32 vcc, 8, v149
	v_cmp_gt_u32_e64 s[26:27], 8, v158
	v_cmp_gt_u32_e64 s[36:37], 8, v159
	v_cmp_gt_u32_e64 s[38:39], 8, v160
	v_med3_i32 v165, v145, 0, 1
	v_med3_i32 v166, v146, 0, 1
	v_med3_i32 v167, v147, 0, 1
	v_med3_i32 v168, v148, 0, 1
	v_cndmask_b32_e64 v161, v161, v149, vcc
	v_cndmask_b32_e64 v162, v162, v158, s[26:27]
	v_cndmask_b32_e64 v163, v163, v159, s[36:37]
	v_cndmask_b32_e64 v164, v164, v160, s[38:39]
	v_lshl_add_u32 v161, v165, 4, v161
	v_lshl_add_u32 v162, v166, 4, v162
	v_lshl_add_u32 v163, v167, 4, v163
	v_lshl_add_u32 v164, v168, 4, v164
	v_lshl_add_u32 v165, v161, 5, v25
	v_lshl_add_u32 v166, v162, 5, v25
	v_lshl_add_u32 v167, v163, 5, v25
	v_lshl_add_u32 v168, v164, 5, v25
	ds_read_b32 v165, v165
	ds_read_b32 v166, v166
	ds_read_b32 v167, v167
	ds_read_b32 v168, v168
	s_waitcnt lgkmcnt(3)
	v_fma_mixlo_f16 v165, v88, s3, v165
	s_waitcnt lgkmcnt(2)
	v_fma_mixlo_f16 v166, v89, s3, v166
	s_waitcnt lgkmcnt(1)
	v_fma_mixlo_f16 v167, v90, s3, v167
	s_waitcnt lgkmcnt(0)
	v_fma_mixlo_f16 v168, v91, s3, v168
	ds_write_b16 v143, v165 offset:3840
	ds_write_b16 v143, v166 offset:3856
	ds_write_b16 v143, v167 offset:3872
	ds_write_b16 v143, v168 offset:3888
	s_mov_b64 exec, s[12:13]
